# GEMM1 k-loop: LDS fragment reads software-pipelined across MFMA groups with two fragment register sets (VGPR alloc 256)
# speedup vs baseline: 1.0067x; 1.0036x over previous
; template <class Epi>
; DI void gemm_phase(const u16* __restrict__ A, const u16* __restrict__ B, int mtiles, int ntiles, char* lds, const Epi& epi) {
;     ...
;         const int lane = tid & 63, wave = __builtin_amdgcn_readfirstlane(tid >> 6); const int wn = wave >> 1, wm = wave & 1; const int r = lane & 31, h = lane >> 5;
;         f32x16 acc[2][2];
; #pragma unroll
;         for (int a = 0; a < 2; ++a)
; #pragma unroll
;             for (int b = 0; b < 2; ++b)
; #pragma unroll
;                 for (int e = 0; e < 16; ++e) acc[a][b][e] = 0.f;
;         unsigned soff[4];
; #pragma unroll
;         for (int i = 0; i < 4; ++i) { const int row = 8 * (i * 4 + wave) + (lane >> 3); const int ch = (lane & 7) ^ ((row >> 1) & 7); soff[i] = (unsigned)(row * 1024 + ch * 8); }
;         const u16* ga = A + (size_t)m0 * 1024; const u16* gb = B + (size_t)n0 * 1024;
;         __syncthreads();
;         for (int kt = 0; kt < 16; ++kt) {
;             if (kt + 1 < 16) GSTAGE((kt + 1) & 1, kt + 1, ga, gb);
;             const char* sa = lds + (kt & 1) * 32768; const char* sb = sa + 16384;
; #pragma unroll
;             for (int ks = 0; ks < 4; ++ks) {
;                 bf16x8 fw[2], fx[2];
; #pragma unroll
;                 for (int ct = 0; ct < 2; ++ct) fw[ct] = *(const bf16x8*)(sb + swz(wn * 64 + ct * 32 + r, 2 * ks + h));
; #pragma unroll
;                 for (int tt = 0; tt < 2; ++tt) fx[tt] = *(const bf16x8*)(sa + swz(wm * 64 + tt * 32 + r, 2 * ks + h));
; #pragma unroll
;                 for (int ct = 0; ct < 2; ++ct)
; #pragma unroll
;                     for (int tt = 0; tt < 2; ++tt) acc[ct][tt] = __builtin_amdgcn_mfma_f32_32x32x16_bf16(fw[ct], fx[tt], acc[ct][tt], 0, 0, 0);
.LBB0_97:
	v_mov_b32_e32 v18, v0
	s_ashr_i32 s83, s82, 31
	v_readfirstlane_b32 s1, v18
	s_ashr_i32 s7, s1, 6
	s_ashr_i32 s4, s1, 7
	s_and_b32 s6, s7, 1
	v_bfe_u32 v2, v18, 3, 3
	s_lshl_b64 s[38:39], s[82:83], 11
	v_lshl_or_b32 v2, s7, 3, v2
	s_add_u32 s38, s54, s38
	v_lshrrev_b32_e32 v3, 1, v2
	s_addc_u32 s39, s55, s39
	s_ashr_i32 s1, s0, 31
	v_xor_b32_e32 v3, v3, v18
	s_lshl_b64 s[50:51], s[0:1], 11
	v_readlane_b32 s1, v236, 9
	v_lshlrev_b32_e32 v2, 10, v2
	v_lshlrev_b32_e32 v3, 3, v3
	s_add_u32 s50, s1, s50
	v_readlane_b32 s1, v236, 11
	v_and_or_b32 v74, v3, 56, v2
	s_addc_u32 s51, s1, s51
	s_lshl_b32 s1, s7, 10
	v_lshlrev_b64 v[66:67], 1, v[74:75]
	s_add_i32 s1, s1, 0
	v_add_u32_e32 v2, 0x8000, v74
	v_bfe_u32 v93, v18, 5, 1
	v_lshrrev_b32_e32 v8, 1, v18
	v_mov_b32_e32 v3, v75
	v_lshl_add_u64 v[76:77], s[38:39], 0, v[66:67]
	s_add_i32 s86, s1, 0x8000
	v_bitop3_b32 v10, v93, v8, 7 bitop3:0x78
	v_lshl_add_u64 v[8:9], v[76:77], 0, s[8:9]
	s_mov_b32 m0, s86
	v_lshl_add_u64 v[78:79], s[50:51], 0, v[66:67]
	s_add_i32 s87, s1, 0xc000
	v_lshlrev_b64 v[68:69], 1, v[2:3]
	v_add_u32_e32 v4, 0x10000, v74
	s_waitcnt vmcnt(0) lgkmcnt(0)
	s_barrier
	v_mov_b32_e32 v5, v75
	global_load_lds_dwordx4 v[8:9], off
	v_lshl_add_u64 v[8:9], v[78:79], 0, s[8:9]
	s_mov_b32 m0, s87
	v_lshl_add_u64 v[80:81], s[38:39], 0, v[68:69]
	s_add_i32 s88, s1, 0x9000
	global_load_lds_dwordx4 v[8:9], off
	v_lshl_add_u64 v[2:3], v[80:81], 0, s[8:9]
	s_mov_b32 m0, s88
	v_lshl_add_u64 v[82:83], s[50:51], 0, v[68:69]
	s_add_i32 s89, s1, 0xd000
	v_lshlrev_b64 v[70:71], 1, v[4:5]
	v_add_u32_e32 v6, 0x18000, v74
	v_mov_b32_e32 v7, v75
	global_load_lds_dwordx4 v[2:3], off
	v_lshl_add_u64 v[2:3], v[82:83], 0, s[8:9]
	s_mov_b32 m0, s89
	v_lshl_add_u64 v[84:85], s[38:39], 0, v[70:71]
	s_add_i32 s91, s1, 0xa000
	global_load_lds_dwordx4 v[2:3], off
	v_lshl_add_u64 v[2:3], v[84:85], 0, s[8:9]
	s_mov_b32 m0, s91
	v_lshl_add_u64 v[86:87], s[50:51], 0, v[70:71]
	s_add_i32 s92, s1, 0xe000
	v_lshlrev_b64 v[72:73], 1, v[6:7]
	global_load_lds_dwordx4 v[2:3], off
	v_lshl_add_u64 v[2:3], v[86:87], 0, s[8:9]
	s_mov_b32 m0, s92
	v_lshl_add_u64 v[88:89], s[38:39], 0, v[72:73]
	s_add_i32 s93, s1, 0xb000
	v_and_b32_e32 v94, 31, v18
	global_load_lds_dwordx4 v[2:3], off
	v_lshl_add_u64 v[2:3], v[88:89], 0, s[8:9]
	s_mov_b32 m0, s93
	v_lshl_add_u64 v[90:91], s[50:51], 0, v[72:73]
	s_add_i32 s94, s1, 0xf000
	s_lshl_b32 s7, s4, 13
	v_lshlrev_b32_e32 v116, 7, v94
	global_load_lds_dwordx4 v[2:3], off
	v_lshl_add_u64 v[2:3], v[90:91], 0, s[8:9]
	s_mov_b32 m0, s94
	v_lshl_add_u32 v6, v10, 4, 0
	global_load_lds_dwordx4 v[2:3], off
	v_add3_u32 v74, v6, s7, v116
	ds_read_b128 v[2:5], v74 offset:16384
	s_lshl_b32 s38, s6, 13
	v_add3_u32 v96, v6, s38, v116
	v_bfe_u32 v117, v18, 1, 3
	ds_read_b128 v[6:9], v96
	ds_read_b128 v[10:13], v96 offset:4096
	ds_read_b128 v[14:17], v74 offset:20480
	v_bitop3_b32 v18, v93, v117, 2 bitop3:0x36
	v_lshl_add_u32 v18, v18, 4, 0
	v_add3_u32 v95, v18, s7, v116
	ds_read_b128 v[50:53], v95 offset:16384
	s_waitcnt lgkmcnt(0)
	v_mfma_f32_32x32x16_bf16 v[34:49], v[2:5], v[6:9], 0
	v_add3_u32 v97, v18, s38, v116
	ds_read_b128 v[98:101], v97
	ds_read_b128 v[102:105], v97 offset:4096
	ds_read_b128 v[106:109], v95 offset:20480
	s_mov_b32 m0, s1
	s_add_i32 s39, s1, 0x5000
	s_add_i32 s50, s1, 0x2000
	s_add_i32 s51, s1, 0x6000
	s_add_i32 s83, s1, 0x3000
	v_mfma_f32_32x32x16_bf16 v[18:33], v[2:5], v[10:13], 0
	s_add_i32 s90, s1, 0x7000
	s_add_i32 s33, s33, s95
	s_waitcnt lgkmcnt(0)
	v_mfma_f32_32x32x16_bf16 v[34:49], v[50:53], v[98:101], v[34:49]
	v_mfma_f32_32x32x16_bf16 v[18:33], v[50:53], v[102:105], v[18:33]
	v_mfma_f32_32x32x16_bf16 v[50:65], v[14:17], v[6:9], 0
	v_mfma_f32_32x32x16_bf16 v[2:17], v[14:17], v[10:13], 0
	v_mfma_f32_32x32x16_bf16 v[50:65], v[106:109], v[98:101], v[50:65]
	v_bitop3_b32 v98, v93, v117, 4 bitop3:0x36
	v_lshl_add_u32 v99, v98, 4, 0
	v_add3_u32 v98, v99, s7, v116
	v_add3_u32 v99, v99, s38, v116
	v_mfma_f32_32x32x16_bf16 v[2:17], v[106:109], v[102:105], v[2:17]
	ds_read_b128 v[100:103], v98 offset:16384
	ds_read_b128 v[104:107], v99
	ds_read_b128 v[108:111], v99 offset:4096
	ds_read_b128 v[112:115], v98 offset:20480
	s_waitcnt lgkmcnt(0)
	v_mfma_f32_32x32x16_bf16 v[34:49], v[100:103], v[104:107], v[34:49]
	v_mfma_f32_32x32x16_bf16 v[18:33], v[100:103], v[108:111], v[18:33]
	v_bitop3_b32 v100, v93, v117, 6 bitop3:0x36
	v_lshl_add_u32 v101, v100, 4, 0
	v_add3_u32 v100, v101, s7, v116
	v_add3_u32 v101, v101, s38, v116
	s_add_i32 s7, s1, 0x4000
	s_add_i32 s38, s1, 0x1000
	s_cmpk_gt_i32 s33, 0x1103
	v_mfma_f32_32x32x16_bf16 v[50:65], v[112:115], v[104:107], v[50:65]
	v_mfma_f32_32x32x16_bf16 v[2:17], v[112:115], v[108:111], v[2:17]
	ds_read_b128 v[238:241], v100 offset:16384
	ds_read_b128 v[242:245], v101
	ds_read_b128 v[246:249], v101 offset:4096
	ds_read_b128 v[250:253], v100 offset:20480
	s_waitcnt vmcnt(0) lgkmcnt(0)
	s_barrier
; template <class Epi>
; DI void gemm_phase(const u16* __restrict__ A, const u16* __restrict__ B, int mtiles, int ntiles, char* lds, const Epi& epi) {
;     ...
;         for (int kt = 0; kt < 16; ++kt) {
;             if (kt + 1 < 16) GSTAGE((kt + 1) & 1, kt + 1, ga, gb);
;             const char* sa = lds + (kt & 1) * 32768; const char* sb = sa + 16384;
; #pragma unroll
;             for (int ks = 0; ks < 4; ++ks) {
;                 bf16x8 fw[2], fx[2];
; #pragma unroll
;                 for (int ct = 0; ct < 2; ++ct) fw[ct] = *(const bf16x8*)(sb + swz(wn * 64 + ct * 32 + r, 2 * ks + h));
; #pragma unroll
;                 for (int tt = 0; tt < 2; ++tt) fx[tt] = *(const bf16x8*)(sa + swz(wm * 64 + tt * 32 + r, 2 * ks + h));
; #pragma unroll
;                 for (int ct = 0; ct < 2; ++ct)
; #pragma unroll
;                     for (int tt = 0; tt < 2; ++tt) acc[ct][tt] = __builtin_amdgcn_mfma_f32_32x32x16_bf16(fw[ct], fx[tt], acc[ct][tt], 0, 0, 0);
;             }
;             __syncthreads();
	ds_read_b128 v[102:105], v74 offset:49152
	ds_read_b128 v[106:109], v96 offset:32768
	ds_read_b128 v[110:113], v96 offset:36864
	ds_read_b128 v[114:117], v74 offset:53248
	v_mfma_f32_32x32x16_bf16 v[34:49], v[238:241], v[242:245], v[34:49]
	v_mfma_f32_32x32x16_bf16 v[18:33], v[238:241], v[246:249], v[18:33]
	v_lshl_add_u64 v[254:255], v[76:77], 0, s[10:11]
	global_load_lds_dwordx4 v[254:255], off
	v_lshl_add_u64 v[254:255], v[78:79], 0, s[10:11]
	s_mov_b32 m0, s7
	s_nop 0
	global_load_lds_dwordx4 v[254:255], off
	v_lshl_add_u64 v[254:255], v[80:81], 0, s[10:11]
	s_mov_b32 m0, s38
	v_mfma_f32_32x32x16_bf16 v[50:65], v[250:253], v[242:245], v[50:65]
	global_load_lds_dwordx4 v[254:255], off
	v_lshl_add_u64 v[254:255], v[82:83], 0, s[10:11]
	s_mov_b32 m0, s39
	s_nop 0
	global_load_lds_dwordx4 v[254:255], off
	v_lshl_add_u64 v[254:255], v[84:85], 0, s[10:11]
	s_mov_b32 m0, s50
	v_mfma_f32_32x32x16_bf16 v[2:17], v[250:253], v[246:249], v[2:17]
	global_load_lds_dwordx4 v[254:255], off
	v_lshl_add_u64 v[254:255], v[86:87], 0, s[10:11]
	s_mov_b32 m0, s51
	s_nop 0
	global_load_lds_dwordx4 v[254:255], off
	v_lshl_add_u64 v[254:255], v[88:89], 0, s[10:11]
	s_mov_b32 m0, s83
	s_nop 0
	global_load_lds_dwordx4 v[254:255], off
	v_lshl_add_u64 v[254:255], v[90:91], 0, s[10:11]
	s_mov_b32 m0, s90
	s_nop 0
	global_load_lds_dwordx4 v[254:255], off
	s_waitcnt lgkmcnt(0)
	ds_read_b128 v[238:241], v95 offset:49152
	ds_read_b128 v[242:245], v97 offset:32768
	ds_read_b128 v[246:249], v97 offset:36864
	ds_read_b128 v[250:253], v95 offset:53248
	v_mfma_f32_32x32x16_bf16 v[34:49], v[102:105], v[106:109], v[34:49]
	s_mov_b32 m0, s86
	v_mfma_f32_32x32x16_bf16 v[18:33], v[102:105], v[110:113], v[18:33]
	v_mfma_f32_32x32x16_bf16 v[50:65], v[114:117], v[106:109], v[50:65]
	v_mfma_f32_32x32x16_bf16 v[2:17], v[114:117], v[110:113], v[2:17]
	s_waitcnt lgkmcnt(0)
	ds_read_b128 v[102:105], v98 offset:49152
	ds_read_b128 v[106:109], v99 offset:32768
	ds_read_b128 v[110:113], v99 offset:36864
	ds_read_b128 v[114:117], v98 offset:53248
	v_mfma_f32_32x32x16_bf16 v[34:49], v[238:241], v[242:245], v[34:49]
	v_mfma_f32_32x32x16_bf16 v[18:33], v[238:241], v[246:249], v[18:33]
	v_mfma_f32_32x32x16_bf16 v[50:65], v[250:253], v[242:245], v[50:65]
	v_mfma_f32_32x32x16_bf16 v[2:17], v[250:253], v[246:249], v[2:17]
	s_waitcnt lgkmcnt(0)
	ds_read_b128 v[238:241], v100 offset:49152
	ds_read_b128 v[242:245], v101 offset:32768
	ds_read_b128 v[246:249], v101 offset:36864
	ds_read_b128 v[250:253], v100 offset:53248
	v_mfma_f32_32x32x16_bf16 v[34:49], v[102:105], v[106:109], v[34:49]
	v_mfma_f32_32x32x16_bf16 v[18:33], v[102:105], v[110:113], v[18:33]
	v_mfma_f32_32x32x16_bf16 v[50:65], v[114:117], v[106:109], v[50:65]
	v_mfma_f32_32x32x16_bf16 v[2:17], v[114:117], v[110:113], v[2:17]
	s_waitcnt vmcnt(0) lgkmcnt(0)
	s_barrier
	ds_read_b128 v[102:105], v74 offset:16384
	ds_read_b128 v[106:109], v96
	ds_read_b128 v[110:113], v96 offset:4096
	ds_read_b128 v[114:117], v74 offset:20480
	v_mfma_f32_32x32x16_bf16 v[34:49], v[238:241], v[242:245], v[34:49]
	v_mfma_f32_32x32x16_bf16 v[18:33], v[238:241], v[246:249], v[18:33]
	v_lshl_add_u64 v[254:255], v[76:77], 0, s[12:13]
	global_load_lds_dwordx4 v[254:255], off
	v_lshl_add_u64 v[254:255], v[78:79], 0, s[12:13]
	s_mov_b32 m0, s87
	s_nop 0
	global_load_lds_dwordx4 v[254:255], off
	v_lshl_add_u64 v[254:255], v[80:81], 0, s[12:13]
	s_mov_b32 m0, s88
	v_mfma_f32_32x32x16_bf16 v[50:65], v[250:253], v[242:245], v[50:65]
	global_load_lds_dwordx4 v[254:255], off
	v_lshl_add_u64 v[254:255], v[82:83], 0, s[12:13]
	s_mov_b32 m0, s89
	s_nop 0
	global_load_lds_dwordx4 v[254:255], off
	v_lshl_add_u64 v[254:255], v[84:85], 0, s[12:13]
	s_mov_b32 m0, s91
	v_mfma_f32_32x32x16_bf16 v[2:17], v[250:253], v[246:249], v[2:17]
	global_load_lds_dwordx4 v[254:255], off
	v_lshl_add_u64 v[254:255], v[86:87], 0, s[12:13]
	s_mov_b32 m0, s92
	s_nop 0
	global_load_lds_dwordx4 v[254:255], off
	v_lshl_add_u64 v[254:255], v[88:89], 0, s[12:13]
	s_mov_b32 m0, s93
	s_nop 0
	global_load_lds_dwordx4 v[254:255], off
	v_lshl_add_u64 v[254:255], v[90:91], 0, s[12:13]
	s_mov_b32 m0, s94
	s_nop 0
	global_load_lds_dwordx4 v[254:255], off
	s_waitcnt lgkmcnt(0)
	ds_read_b128 v[238:241], v95 offset:16384
	ds_read_b128 v[242:245], v97
	ds_read_b128 v[246:249], v97 offset:4096
	ds_read_b128 v[250:253], v95 offset:20480
	v_mfma_f32_32x32x16_bf16 v[34:49], v[102:105], v[106:109], v[34:49]
	s_mov_b32 m0, s1
	v_mfma_f32_32x32x16_bf16 v[18:33], v[102:105], v[110:113], v[18:33]
	v_mfma_f32_32x32x16_bf16 v[50:65], v[114:117], v[106:109], v[50:65]
	v_mfma_f32_32x32x16_bf16 v[2:17], v[114:117], v[110:113], v[2:17]
	s_waitcnt lgkmcnt(0)
	ds_read_b128 v[102:105], v98 offset:16384
	ds_read_b128 v[106:109], v99
	ds_read_b128 v[110:113], v99 offset:4096
	ds_read_b128 v[114:117], v98 offset:20480
	v_mfma_f32_32x32x16_bf16 v[34:49], v[238:241], v[242:245], v[34:49]
	v_mfma_f32_32x32x16_bf16 v[18:33], v[238:241], v[246:249], v[18:33]
	v_mfma_f32_32x32x16_bf16 v[50:65], v[250:253], v[242:245], v[50:65]
	v_mfma_f32_32x32x16_bf16 v[2:17], v[250:253], v[246:249], v[2:17]
	s_waitcnt lgkmcnt(0)
	ds_read_b128 v[238:241], v100 offset:16384
	ds_read_b128 v[242:245], v101
	ds_read_b128 v[246:249], v101 offset:4096
	ds_read_b128 v[250:253], v100 offset:20480
	v_mfma_f32_32x32x16_bf16 v[34:49], v[102:105], v[106:109], v[34:49]
	v_mfma_f32_32x32x16_bf16 v[18:33], v[102:105], v[110:113], v[18:33]
	v_mfma_f32_32x32x16_bf16 v[50:65], v[114:117], v[106:109], v[50:65]
	v_mfma_f32_32x32x16_bf16 v[2:17], v[114:117], v[110:113], v[2:17]
	s_waitcnt vmcnt(0) lgkmcnt(0)
	s_barrier
; template <class Epi>
; DI void gemm_phase(const u16* __restrict__ A, const u16* __restrict__ B, int mtiles, int ntiles, char* lds, const Epi& epi) {
;     ...
;         for (int kt = 0; kt < 16; ++kt) {
;             if (kt + 1 < 16) GSTAGE((kt + 1) & 1, kt + 1, ga, gb);
;             const char* sa = lds + (kt & 1) * 32768; const char* sb = sa + 16384;
; #pragma unroll
;             for (int ks = 0; ks < 4; ++ks) {
;                 bf16x8 fw[2], fx[2];
; #pragma unroll
;                 for (int ct = 0; ct < 2; ++ct) fw[ct] = *(const bf16x8*)(sb + swz(wn * 64 + ct * 32 + r, 2 * ks + h));
; #pragma unroll
;                 for (int tt = 0; tt < 2; ++tt) fx[tt] = *(const bf16x8*)(sa + swz(wm * 64 + tt * 32 + r, 2 * ks + h));
; #pragma unroll
;                 for (int ct = 0; ct < 2; ++ct)
; #pragma unroll
;                     for (int tt = 0; tt < 2; ++tt) acc[ct][tt] = __builtin_amdgcn_mfma_f32_32x32x16_bf16(fw[ct], fx[tt], acc[ct][tt], 0, 0, 0);
;             }
;             __syncthreads();
	ds_read_b128 v[102:105], v74 offset:49152
	ds_read_b128 v[106:109], v96 offset:32768
	ds_read_b128 v[110:113], v96 offset:36864
	ds_read_b128 v[114:117], v74 offset:53248
	v_mfma_f32_32x32x16_bf16 v[34:49], v[238:241], v[242:245], v[34:49]
	v_mfma_f32_32x32x16_bf16 v[18:33], v[238:241], v[246:249], v[18:33]
	v_lshl_add_u64 v[254:255], v[76:77], 0, s[14:15]
	global_load_lds_dwordx4 v[254:255], off
	v_lshl_add_u64 v[254:255], v[78:79], 0, s[14:15]
	s_mov_b32 m0, s7
	s_nop 0
	global_load_lds_dwordx4 v[254:255], off
	v_lshl_add_u64 v[254:255], v[80:81], 0, s[14:15]
	s_mov_b32 m0, s38
	v_mfma_f32_32x32x16_bf16 v[50:65], v[250:253], v[242:245], v[50:65]
	global_load_lds_dwordx4 v[254:255], off
	v_lshl_add_u64 v[254:255], v[82:83], 0, s[14:15]
	s_mov_b32 m0, s39
	s_nop 0
	global_load_lds_dwordx4 v[254:255], off
	v_lshl_add_u64 v[254:255], v[84:85], 0, s[14:15]
	s_mov_b32 m0, s50
	v_mfma_f32_32x32x16_bf16 v[2:17], v[250:253], v[246:249], v[2:17]
	global_load_lds_dwordx4 v[254:255], off
	v_lshl_add_u64 v[254:255], v[86:87], 0, s[14:15]
	s_mov_b32 m0, s51
	s_nop 0
	global_load_lds_dwordx4 v[254:255], off
	v_lshl_add_u64 v[254:255], v[88:89], 0, s[14:15]
	s_mov_b32 m0, s83
	s_nop 0
	global_load_lds_dwordx4 v[254:255], off
	v_lshl_add_u64 v[254:255], v[90:91], 0, s[14:15]
	s_mov_b32 m0, s90
	s_nop 0
	global_load_lds_dwordx4 v[254:255], off
	s_waitcnt lgkmcnt(0)
	ds_read_b128 v[238:241], v95 offset:49152
	ds_read_b128 v[242:245], v97 offset:32768
	ds_read_b128 v[246:249], v97 offset:36864
	ds_read_b128 v[250:253], v95 offset:53248
	v_mfma_f32_32x32x16_bf16 v[34:49], v[102:105], v[106:109], v[34:49]
	s_mov_b32 m0, s86
	v_mfma_f32_32x32x16_bf16 v[18:33], v[102:105], v[110:113], v[18:33]
	v_mfma_f32_32x32x16_bf16 v[50:65], v[114:117], v[106:109], v[50:65]
	v_mfma_f32_32x32x16_bf16 v[2:17], v[114:117], v[110:113], v[2:17]
	s_waitcnt lgkmcnt(0)
	ds_read_b128 v[102:105], v98 offset:49152
	ds_read_b128 v[106:109], v99 offset:32768
	ds_read_b128 v[110:113], v99 offset:36864
	ds_read_b128 v[114:117], v98 offset:53248
	v_mfma_f32_32x32x16_bf16 v[34:49], v[238:241], v[242:245], v[34:49]
	v_mfma_f32_32x32x16_bf16 v[18:33], v[238:241], v[246:249], v[18:33]
	v_mfma_f32_32x32x16_bf16 v[50:65], v[250:253], v[242:245], v[50:65]
	v_mfma_f32_32x32x16_bf16 v[2:17], v[250:253], v[246:249], v[2:17]
	s_waitcnt lgkmcnt(0)
	ds_read_b128 v[238:241], v100 offset:49152
	ds_read_b128 v[242:245], v101 offset:32768
	ds_read_b128 v[246:249], v101 offset:36864
	ds_read_b128 v[250:253], v100 offset:53248
	v_mfma_f32_32x32x16_bf16 v[34:49], v[102:105], v[106:109], v[34:49]
	v_mfma_f32_32x32x16_bf16 v[18:33], v[102:105], v[110:113], v[18:33]
	v_mfma_f32_32x32x16_bf16 v[50:65], v[114:117], v[106:109], v[50:65]
	v_mfma_f32_32x32x16_bf16 v[2:17], v[114:117], v[110:113], v[2:17]
	s_waitcnt vmcnt(0) lgkmcnt(0)
	s_barrier
	ds_read_b128 v[102:105], v74 offset:16384
	ds_read_b128 v[106:109], v96
	ds_read_b128 v[110:113], v96 offset:4096
	ds_read_b128 v[114:117], v74 offset:20480
	v_mfma_f32_32x32x16_bf16 v[34:49], v[238:241], v[242:245], v[34:49]
	v_mfma_f32_32x32x16_bf16 v[18:33], v[238:241], v[246:249], v[18:33]
	v_lshl_add_u64 v[254:255], v[76:77], 0, s[16:17]
	global_load_lds_dwordx4 v[254:255], off
	v_lshl_add_u64 v[254:255], v[78:79], 0, s[16:17]
	s_mov_b32 m0, s87
	s_nop 0
	global_load_lds_dwordx4 v[254:255], off
	v_lshl_add_u64 v[254:255], v[80:81], 0, s[16:17]
	s_mov_b32 m0, s88
	v_mfma_f32_32x32x16_bf16 v[50:65], v[250:253], v[242:245], v[50:65]
	global_load_lds_dwordx4 v[254:255], off
	v_lshl_add_u64 v[254:255], v[82:83], 0, s[16:17]
	s_mov_b32 m0, s89
	s_nop 0
	global_load_lds_dwordx4 v[254:255], off
	v_lshl_add_u64 v[254:255], v[84:85], 0, s[16:17]
	s_mov_b32 m0, s91
	v_mfma_f32_32x32x16_bf16 v[2:17], v[250:253], v[246:249], v[2:17]
	global_load_lds_dwordx4 v[254:255], off
	v_lshl_add_u64 v[254:255], v[86:87], 0, s[16:17]
	s_mov_b32 m0, s92
	s_nop 0
	global_load_lds_dwordx4 v[254:255], off
	v_lshl_add_u64 v[254:255], v[88:89], 0, s[16:17]
	s_mov_b32 m0, s93
	s_nop 0
	global_load_lds_dwordx4 v[254:255], off
	v_lshl_add_u64 v[254:255], v[90:91], 0, s[16:17]
	s_mov_b32 m0, s94
	s_nop 0
	global_load_lds_dwordx4 v[254:255], off
	s_waitcnt lgkmcnt(0)
	ds_read_b128 v[238:241], v95 offset:16384
	ds_read_b128 v[242:245], v97
	ds_read_b128 v[246:249], v97 offset:4096
	ds_read_b128 v[250:253], v95 offset:20480
	v_mfma_f32_32x32x16_bf16 v[34:49], v[102:105], v[106:109], v[34:49]
	s_mov_b32 m0, s1
	v_mfma_f32_32x32x16_bf16 v[18:33], v[102:105], v[110:113], v[18:33]
	v_mfma_f32_32x32x16_bf16 v[50:65], v[114:117], v[106:109], v[50:65]
	v_mfma_f32_32x32x16_bf16 v[2:17], v[114:117], v[110:113], v[2:17]
	s_waitcnt lgkmcnt(0)
	ds_read_b128 v[102:105], v98 offset:16384
	ds_read_b128 v[106:109], v99
	ds_read_b128 v[110:113], v99 offset:4096
	ds_read_b128 v[114:117], v98 offset:20480
	v_mfma_f32_32x32x16_bf16 v[34:49], v[238:241], v[242:245], v[34:49]
	v_mfma_f32_32x32x16_bf16 v[18:33], v[238:241], v[246:249], v[18:33]
	v_mfma_f32_32x32x16_bf16 v[50:65], v[250:253], v[242:245], v[50:65]
	v_mfma_f32_32x32x16_bf16 v[2:17], v[250:253], v[246:249], v[2:17]
	s_waitcnt lgkmcnt(0)
	ds_read_b128 v[238:241], v100 offset:16384
	ds_read_b128 v[242:245], v101
	ds_read_b128 v[246:249], v101 offset:4096
	ds_read_b128 v[250:253], v100 offset:20480
	v_mfma_f32_32x32x16_bf16 v[34:49], v[102:105], v[106:109], v[34:49]
	v_mfma_f32_32x32x16_bf16 v[18:33], v[102:105], v[110:113], v[18:33]
	v_mfma_f32_32x32x16_bf16 v[50:65], v[114:117], v[106:109], v[50:65]
	v_mfma_f32_32x32x16_bf16 v[2:17], v[114:117], v[110:113], v[2:17]
	s_waitcnt vmcnt(0) lgkmcnt(0)
	s_barrier
; template <class Epi>
; DI void gemm_phase(const u16* __restrict__ A, const u16* __restrict__ B, int mtiles, int ntiles, char* lds, const Epi& epi) {
;     ...
;         for (int kt = 0; kt < 16; ++kt) {
;             if (kt + 1 < 16) GSTAGE((kt + 1) & 1, kt + 1, ga, gb);
;             const char* sa = lds + (kt & 1) * 32768; const char* sb = sa + 16384;
; #pragma unroll
;             for (int ks = 0; ks < 4; ++ks) {
;                 bf16x8 fw[2], fx[2];
; #pragma unroll
;                 for (int ct = 0; ct < 2; ++ct) fw[ct] = *(const bf16x8*)(sb + swz(wn * 64 + ct * 32 + r, 2 * ks + h));
; #pragma unroll
;                 for (int tt = 0; tt < 2; ++tt) fx[tt] = *(const bf16x8*)(sa + swz(wm * 64 + tt * 32 + r, 2 * ks + h));
; #pragma unroll
;                 for (int ct = 0; ct < 2; ++ct)
; #pragma unroll
;                     for (int tt = 0; tt < 2; ++tt) acc[ct][tt] = __builtin_amdgcn_mfma_f32_32x32x16_bf16(fw[ct], fx[tt], acc[ct][tt], 0, 0, 0);
;             }
;             __syncthreads();
	ds_read_b128 v[102:105], v74 offset:49152
	ds_read_b128 v[106:109], v96 offset:32768
	ds_read_b128 v[110:113], v96 offset:36864
	ds_read_b128 v[114:117], v74 offset:53248
	v_mfma_f32_32x32x16_bf16 v[34:49], v[238:241], v[242:245], v[34:49]
	v_mfma_f32_32x32x16_bf16 v[18:33], v[238:241], v[246:249], v[18:33]
	v_lshl_add_u64 v[254:255], v[76:77], 0, s[18:19]
	global_load_lds_dwordx4 v[254:255], off
	v_lshl_add_u64 v[254:255], v[78:79], 0, s[18:19]
	s_mov_b32 m0, s7
	s_nop 0
	global_load_lds_dwordx4 v[254:255], off
	v_lshl_add_u64 v[254:255], v[80:81], 0, s[18:19]
	s_mov_b32 m0, s38
	v_mfma_f32_32x32x16_bf16 v[50:65], v[250:253], v[242:245], v[50:65]
	global_load_lds_dwordx4 v[254:255], off
	v_lshl_add_u64 v[254:255], v[82:83], 0, s[18:19]
	s_mov_b32 m0, s39
	s_nop 0
	global_load_lds_dwordx4 v[254:255], off
	v_lshl_add_u64 v[254:255], v[84:85], 0, s[18:19]
	s_mov_b32 m0, s50
	v_mfma_f32_32x32x16_bf16 v[2:17], v[250:253], v[246:249], v[2:17]
	global_load_lds_dwordx4 v[254:255], off
	v_lshl_add_u64 v[254:255], v[86:87], 0, s[18:19]
	s_mov_b32 m0, s51
	s_nop 0
	global_load_lds_dwordx4 v[254:255], off
	v_lshl_add_u64 v[254:255], v[88:89], 0, s[18:19]
	s_mov_b32 m0, s83
	s_nop 0
	global_load_lds_dwordx4 v[254:255], off
	v_lshl_add_u64 v[254:255], v[90:91], 0, s[18:19]
	s_mov_b32 m0, s90
	s_nop 0
	global_load_lds_dwordx4 v[254:255], off
	s_waitcnt lgkmcnt(0)
	ds_read_b128 v[238:241], v95 offset:49152
	ds_read_b128 v[242:245], v97 offset:32768
	ds_read_b128 v[246:249], v97 offset:36864
	ds_read_b128 v[250:253], v95 offset:53248
	v_mfma_f32_32x32x16_bf16 v[34:49], v[102:105], v[106:109], v[34:49]
	s_mov_b32 m0, s86
	v_mfma_f32_32x32x16_bf16 v[18:33], v[102:105], v[110:113], v[18:33]
	v_mfma_f32_32x32x16_bf16 v[50:65], v[114:117], v[106:109], v[50:65]
	v_mfma_f32_32x32x16_bf16 v[2:17], v[114:117], v[110:113], v[2:17]
	s_waitcnt lgkmcnt(0)
	ds_read_b128 v[102:105], v98 offset:49152
	ds_read_b128 v[106:109], v99 offset:32768
	ds_read_b128 v[110:113], v99 offset:36864
	ds_read_b128 v[114:117], v98 offset:53248
	v_mfma_f32_32x32x16_bf16 v[34:49], v[238:241], v[242:245], v[34:49]
	v_mfma_f32_32x32x16_bf16 v[18:33], v[238:241], v[246:249], v[18:33]
	v_mfma_f32_32x32x16_bf16 v[50:65], v[250:253], v[242:245], v[50:65]
	v_mfma_f32_32x32x16_bf16 v[2:17], v[250:253], v[246:249], v[2:17]
	s_waitcnt lgkmcnt(0)
	ds_read_b128 v[238:241], v100 offset:49152
	ds_read_b128 v[242:245], v101 offset:32768
	ds_read_b128 v[246:249], v101 offset:36864
	ds_read_b128 v[250:253], v100 offset:53248
	v_mfma_f32_32x32x16_bf16 v[34:49], v[102:105], v[106:109], v[34:49]
	v_mfma_f32_32x32x16_bf16 v[18:33], v[102:105], v[110:113], v[18:33]
	v_mfma_f32_32x32x16_bf16 v[50:65], v[114:117], v[106:109], v[50:65]
	v_mfma_f32_32x32x16_bf16 v[2:17], v[114:117], v[110:113], v[2:17]
	s_waitcnt vmcnt(0) lgkmcnt(0)
	s_barrier
	ds_read_b128 v[102:105], v74 offset:16384
	ds_read_b128 v[106:109], v96
	ds_read_b128 v[110:113], v96 offset:4096
	ds_read_b128 v[114:117], v74 offset:20480
	v_mfma_f32_32x32x16_bf16 v[34:49], v[238:241], v[242:245], v[34:49]
	v_mfma_f32_32x32x16_bf16 v[18:33], v[238:241], v[246:249], v[18:33]
	v_lshl_add_u64 v[254:255], v[76:77], 0, s[20:21]
	global_load_lds_dwordx4 v[254:255], off
	v_lshl_add_u64 v[254:255], v[78:79], 0, s[20:21]
	s_mov_b32 m0, s87
	s_nop 0
	global_load_lds_dwordx4 v[254:255], off
	v_lshl_add_u64 v[254:255], v[80:81], 0, s[20:21]
	s_mov_b32 m0, s88
	v_mfma_f32_32x32x16_bf16 v[50:65], v[250:253], v[242:245], v[50:65]
	global_load_lds_dwordx4 v[254:255], off
	v_lshl_add_u64 v[254:255], v[82:83], 0, s[20:21]
	s_mov_b32 m0, s89
	s_nop 0
	global_load_lds_dwordx4 v[254:255], off
	v_lshl_add_u64 v[254:255], v[84:85], 0, s[20:21]
	s_mov_b32 m0, s91
	v_mfma_f32_32x32x16_bf16 v[2:17], v[250:253], v[246:249], v[2:17]
	global_load_lds_dwordx4 v[254:255], off
	v_lshl_add_u64 v[254:255], v[86:87], 0, s[20:21]
	s_mov_b32 m0, s92
	s_nop 0
	global_load_lds_dwordx4 v[254:255], off
	v_lshl_add_u64 v[254:255], v[88:89], 0, s[20:21]
	s_mov_b32 m0, s93
	s_nop 0
	global_load_lds_dwordx4 v[254:255], off
	v_lshl_add_u64 v[254:255], v[90:91], 0, s[20:21]
	s_mov_b32 m0, s94
	s_nop 0
	global_load_lds_dwordx4 v[254:255], off
	s_waitcnt lgkmcnt(0)
	ds_read_b128 v[238:241], v95 offset:16384
	ds_read_b128 v[242:245], v97
	ds_read_b128 v[246:249], v97 offset:4096
	ds_read_b128 v[250:253], v95 offset:20480
	v_mfma_f32_32x32x16_bf16 v[34:49], v[102:105], v[106:109], v[34:49]
	s_mov_b32 m0, s1
	v_mfma_f32_32x32x16_bf16 v[18:33], v[102:105], v[110:113], v[18:33]
	v_mfma_f32_32x32x16_bf16 v[50:65], v[114:117], v[106:109], v[50:65]
	v_mfma_f32_32x32x16_bf16 v[2:17], v[114:117], v[110:113], v[2:17]
	s_waitcnt lgkmcnt(0)
	ds_read_b128 v[102:105], v98 offset:16384
	ds_read_b128 v[106:109], v99
	ds_read_b128 v[110:113], v99 offset:4096
	ds_read_b128 v[114:117], v98 offset:20480
	v_mfma_f32_32x32x16_bf16 v[34:49], v[238:241], v[242:245], v[34:49]
	v_mfma_f32_32x32x16_bf16 v[18:33], v[238:241], v[246:249], v[18:33]
	v_mfma_f32_32x32x16_bf16 v[50:65], v[250:253], v[242:245], v[50:65]
	v_mfma_f32_32x32x16_bf16 v[2:17], v[250:253], v[246:249], v[2:17]
	s_waitcnt lgkmcnt(0)
	ds_read_b128 v[238:241], v100 offset:16384
	ds_read_b128 v[242:245], v101
	ds_read_b128 v[246:249], v101 offset:4096
	ds_read_b128 v[250:253], v100 offset:20480
	v_mfma_f32_32x32x16_bf16 v[34:49], v[102:105], v[106:109], v[34:49]
	v_mfma_f32_32x32x16_bf16 v[18:33], v[102:105], v[110:113], v[18:33]
	v_mfma_f32_32x32x16_bf16 v[50:65], v[114:117], v[106:109], v[50:65]
	v_mfma_f32_32x32x16_bf16 v[2:17], v[114:117], v[110:113], v[2:17]
	s_waitcnt vmcnt(0) lgkmcnt(0)
	s_barrier
; template <class Epi>
; DI void gemm_phase(const u16* __restrict__ A, const u16* __restrict__ B, int mtiles, int ntiles, char* lds, const Epi& epi) {
;     ...
;         for (int kt = 0; kt < 16; ++kt) {
;             if (kt + 1 < 16) GSTAGE((kt + 1) & 1, kt + 1, ga, gb);
;             const char* sa = lds + (kt & 1) * 32768; const char* sb = sa + 16384;
; #pragma unroll
;             for (int ks = 0; ks < 4; ++ks) {
;                 bf16x8 fw[2], fx[2];
; #pragma unroll
;                 for (int ct = 0; ct < 2; ++ct) fw[ct] = *(const bf16x8*)(sb + swz(wn * 64 + ct * 32 + r, 2 * ks + h));
; #pragma unroll
;                 for (int tt = 0; tt < 2; ++tt) fx[tt] = *(const bf16x8*)(sa + swz(wm * 64 + tt * 32 + r, 2 * ks + h));
; #pragma unroll
;                 for (int ct = 0; ct < 2; ++ct)
; #pragma unroll
;                     for (int tt = 0; tt < 2; ++tt) acc[ct][tt] = __builtin_amdgcn_mfma_f32_32x32x16_bf16(fw[ct], fx[tt], acc[ct][tt], 0, 0, 0);
;             }
;             __syncthreads();
	ds_read_b128 v[102:105], v74 offset:49152
	ds_read_b128 v[106:109], v96 offset:32768
	ds_read_b128 v[110:113], v96 offset:36864
	ds_read_b128 v[114:117], v74 offset:53248
	v_mfma_f32_32x32x16_bf16 v[34:49], v[238:241], v[242:245], v[34:49]
	v_mfma_f32_32x32x16_bf16 v[18:33], v[238:241], v[246:249], v[18:33]
	v_lshl_add_u64 v[254:255], v[76:77], 0, s[22:23]
	global_load_lds_dwordx4 v[254:255], off
	v_lshl_add_u64 v[254:255], v[78:79], 0, s[22:23]
	s_mov_b32 m0, s7
	s_nop 0
	global_load_lds_dwordx4 v[254:255], off
	v_lshl_add_u64 v[254:255], v[80:81], 0, s[22:23]
	s_mov_b32 m0, s38
	v_mfma_f32_32x32x16_bf16 v[50:65], v[250:253], v[242:245], v[50:65]
	global_load_lds_dwordx4 v[254:255], off
	v_lshl_add_u64 v[254:255], v[82:83], 0, s[22:23]
	s_mov_b32 m0, s39
	s_nop 0
	global_load_lds_dwordx4 v[254:255], off
	v_lshl_add_u64 v[254:255], v[84:85], 0, s[22:23]
	s_mov_b32 m0, s50
	v_mfma_f32_32x32x16_bf16 v[2:17], v[250:253], v[246:249], v[2:17]
	global_load_lds_dwordx4 v[254:255], off
	v_lshl_add_u64 v[254:255], v[86:87], 0, s[22:23]
	s_mov_b32 m0, s51
	s_nop 0
	global_load_lds_dwordx4 v[254:255], off
	v_lshl_add_u64 v[254:255], v[88:89], 0, s[22:23]
	s_mov_b32 m0, s83
	s_nop 0
	global_load_lds_dwordx4 v[254:255], off
	v_lshl_add_u64 v[254:255], v[90:91], 0, s[22:23]
	s_mov_b32 m0, s90
	s_nop 0
	global_load_lds_dwordx4 v[254:255], off
	s_waitcnt lgkmcnt(0)
	ds_read_b128 v[238:241], v95 offset:49152
	ds_read_b128 v[242:245], v97 offset:32768
	ds_read_b128 v[246:249], v97 offset:36864
	ds_read_b128 v[250:253], v95 offset:53248
	v_mfma_f32_32x32x16_bf16 v[34:49], v[102:105], v[106:109], v[34:49]
	s_mov_b32 m0, s86
	v_mfma_f32_32x32x16_bf16 v[18:33], v[102:105], v[110:113], v[18:33]
	v_mfma_f32_32x32x16_bf16 v[50:65], v[114:117], v[106:109], v[50:65]
	v_mfma_f32_32x32x16_bf16 v[2:17], v[114:117], v[110:113], v[2:17]
	s_waitcnt lgkmcnt(0)
	ds_read_b128 v[102:105], v98 offset:49152
	ds_read_b128 v[106:109], v99 offset:32768
	ds_read_b128 v[110:113], v99 offset:36864
	ds_read_b128 v[114:117], v98 offset:53248
	v_mfma_f32_32x32x16_bf16 v[34:49], v[238:241], v[242:245], v[34:49]
	v_mfma_f32_32x32x16_bf16 v[18:33], v[238:241], v[246:249], v[18:33]
	v_mfma_f32_32x32x16_bf16 v[50:65], v[250:253], v[242:245], v[50:65]
	v_mfma_f32_32x32x16_bf16 v[2:17], v[250:253], v[246:249], v[2:17]
	s_waitcnt lgkmcnt(0)
	ds_read_b128 v[238:241], v100 offset:49152
	ds_read_b128 v[242:245], v101 offset:32768
	ds_read_b128 v[246:249], v101 offset:36864
	ds_read_b128 v[250:253], v100 offset:53248
	v_mfma_f32_32x32x16_bf16 v[34:49], v[102:105], v[106:109], v[34:49]
	v_mfma_f32_32x32x16_bf16 v[18:33], v[102:105], v[110:113], v[18:33]
	v_mfma_f32_32x32x16_bf16 v[50:65], v[114:117], v[106:109], v[50:65]
	v_mfma_f32_32x32x16_bf16 v[2:17], v[114:117], v[110:113], v[2:17]
	s_waitcnt vmcnt(0) lgkmcnt(0)
	s_barrier
	ds_read_b128 v[102:105], v74 offset:16384
	ds_read_b128 v[106:109], v96
	ds_read_b128 v[110:113], v96 offset:4096
	ds_read_b128 v[114:117], v74 offset:20480
	v_mfma_f32_32x32x16_bf16 v[34:49], v[238:241], v[242:245], v[34:49]
	v_mfma_f32_32x32x16_bf16 v[18:33], v[238:241], v[246:249], v[18:33]
	v_lshl_add_u64 v[254:255], v[76:77], 0, s[24:25]
	global_load_lds_dwordx4 v[254:255], off
	v_lshl_add_u64 v[254:255], v[78:79], 0, s[24:25]
	s_mov_b32 m0, s87
	s_nop 0
	global_load_lds_dwordx4 v[254:255], off
	v_lshl_add_u64 v[254:255], v[80:81], 0, s[24:25]
	s_mov_b32 m0, s88
	v_mfma_f32_32x32x16_bf16 v[50:65], v[250:253], v[242:245], v[50:65]
	global_load_lds_dwordx4 v[254:255], off
	v_lshl_add_u64 v[254:255], v[82:83], 0, s[24:25]
	s_mov_b32 m0, s89
	s_nop 0
	global_load_lds_dwordx4 v[254:255], off
	v_lshl_add_u64 v[254:255], v[84:85], 0, s[24:25]
	s_mov_b32 m0, s91
	v_mfma_f32_32x32x16_bf16 v[2:17], v[250:253], v[246:249], v[2:17]
	global_load_lds_dwordx4 v[254:255], off
	v_lshl_add_u64 v[254:255], v[86:87], 0, s[24:25]
	s_mov_b32 m0, s92
	s_nop 0
	global_load_lds_dwordx4 v[254:255], off
	v_lshl_add_u64 v[254:255], v[88:89], 0, s[24:25]
	s_mov_b32 m0, s93
	s_nop 0
	global_load_lds_dwordx4 v[254:255], off
	v_lshl_add_u64 v[254:255], v[90:91], 0, s[24:25]
	s_mov_b32 m0, s94
	s_nop 0
	global_load_lds_dwordx4 v[254:255], off
	s_waitcnt lgkmcnt(0)
	ds_read_b128 v[238:241], v95 offset:16384
	ds_read_b128 v[242:245], v97
	ds_read_b128 v[246:249], v97 offset:4096
	ds_read_b128 v[250:253], v95 offset:20480
	v_mfma_f32_32x32x16_bf16 v[34:49], v[102:105], v[106:109], v[34:49]
	s_mov_b32 m0, s1
	v_mfma_f32_32x32x16_bf16 v[18:33], v[102:105], v[110:113], v[18:33]
	v_mfma_f32_32x32x16_bf16 v[50:65], v[114:117], v[106:109], v[50:65]
	v_mfma_f32_32x32x16_bf16 v[2:17], v[114:117], v[110:113], v[2:17]
	s_waitcnt lgkmcnt(0)
	ds_read_b128 v[102:105], v98 offset:16384
	ds_read_b128 v[106:109], v99
	ds_read_b128 v[110:113], v99 offset:4096
	ds_read_b128 v[114:117], v98 offset:20480
	v_mfma_f32_32x32x16_bf16 v[34:49], v[238:241], v[242:245], v[34:49]
	v_mfma_f32_32x32x16_bf16 v[18:33], v[238:241], v[246:249], v[18:33]
	v_mfma_f32_32x32x16_bf16 v[50:65], v[250:253], v[242:245], v[50:65]
	v_mfma_f32_32x32x16_bf16 v[2:17], v[250:253], v[246:249], v[2:17]
	s_waitcnt lgkmcnt(0)
	ds_read_b128 v[238:241], v100 offset:16384
	ds_read_b128 v[242:245], v101
	ds_read_b128 v[246:249], v101 offset:4096
	ds_read_b128 v[250:253], v100 offset:20480
	v_mfma_f32_32x32x16_bf16 v[34:49], v[102:105], v[106:109], v[34:49]
	v_mfma_f32_32x32x16_bf16 v[18:33], v[102:105], v[110:113], v[18:33]
	v_mfma_f32_32x32x16_bf16 v[50:65], v[114:117], v[106:109], v[50:65]
	v_mfma_f32_32x32x16_bf16 v[2:17], v[114:117], v[110:113], v[2:17]
	s_waitcnt vmcnt(0) lgkmcnt(0)
	s_barrier
; template <class Epi>
; DI void gemm_phase(const u16* __restrict__ A, const u16* __restrict__ B, int mtiles, int ntiles, char* lds, const Epi& epi) {
;     ...
;         for (int kt = 0; kt < 16; ++kt) {
;             if (kt + 1 < 16) GSTAGE((kt + 1) & 1, kt + 1, ga, gb);
;             const char* sa = lds + (kt & 1) * 32768; const char* sb = sa + 16384;
; #pragma unroll
;             for (int ks = 0; ks < 4; ++ks) {
;                 bf16x8 fw[2], fx[2];
; #pragma unroll
;                 for (int ct = 0; ct < 2; ++ct) fw[ct] = *(const bf16x8*)(sb + swz(wn * 64 + ct * 32 + r, 2 * ks + h));
; #pragma unroll
;                 for (int tt = 0; tt < 2; ++tt) fx[tt] = *(const bf16x8*)(sa + swz(wm * 64 + tt * 32 + r, 2 * ks + h));
; #pragma unroll
;                 for (int ct = 0; ct < 2; ++ct)
; #pragma unroll
;                     for (int tt = 0; tt < 2; ++tt) acc[ct][tt] = __builtin_amdgcn_mfma_f32_32x32x16_bf16(fw[ct], fx[tt], acc[ct][tt], 0, 0, 0);
;             }
;             __syncthreads();
	ds_read_b128 v[102:105], v74 offset:49152
	ds_read_b128 v[106:109], v96 offset:32768
	ds_read_b128 v[110:113], v96 offset:36864
	ds_read_b128 v[114:117], v74 offset:53248
	v_mfma_f32_32x32x16_bf16 v[34:49], v[238:241], v[242:245], v[34:49]
	v_mfma_f32_32x32x16_bf16 v[18:33], v[238:241], v[246:249], v[18:33]
	v_lshl_add_u64 v[254:255], v[76:77], 0, s[26:27]
	global_load_lds_dwordx4 v[254:255], off
	v_lshl_add_u64 v[254:255], v[78:79], 0, s[26:27]
	s_mov_b32 m0, s7
	s_nop 0
	global_load_lds_dwordx4 v[254:255], off
	v_lshl_add_u64 v[254:255], v[80:81], 0, s[26:27]
	s_mov_b32 m0, s38
	v_mfma_f32_32x32x16_bf16 v[50:65], v[250:253], v[242:245], v[50:65]
	global_load_lds_dwordx4 v[254:255], off
	v_lshl_add_u64 v[254:255], v[82:83], 0, s[26:27]
	s_mov_b32 m0, s39
	s_nop 0
	global_load_lds_dwordx4 v[254:255], off
	v_lshl_add_u64 v[254:255], v[84:85], 0, s[26:27]
	s_mov_b32 m0, s50
	v_mfma_f32_32x32x16_bf16 v[2:17], v[250:253], v[246:249], v[2:17]
	global_load_lds_dwordx4 v[254:255], off
	v_lshl_add_u64 v[254:255], v[86:87], 0, s[26:27]
	s_mov_b32 m0, s51
	s_nop 0
	global_load_lds_dwordx4 v[254:255], off
	v_lshl_add_u64 v[254:255], v[88:89], 0, s[26:27]
	s_mov_b32 m0, s83
	s_nop 0
	global_load_lds_dwordx4 v[254:255], off
	v_lshl_add_u64 v[254:255], v[90:91], 0, s[26:27]
	s_mov_b32 m0, s90
	s_nop 0
	global_load_lds_dwordx4 v[254:255], off
	s_waitcnt lgkmcnt(0)
	ds_read_b128 v[238:241], v95 offset:49152
	ds_read_b128 v[242:245], v97 offset:32768
	ds_read_b128 v[246:249], v97 offset:36864
	ds_read_b128 v[250:253], v95 offset:53248
	v_mfma_f32_32x32x16_bf16 v[34:49], v[102:105], v[106:109], v[34:49]
	s_mov_b32 m0, s86
	v_mfma_f32_32x32x16_bf16 v[18:33], v[102:105], v[110:113], v[18:33]
	v_mfma_f32_32x32x16_bf16 v[50:65], v[114:117], v[106:109], v[50:65]
	v_mfma_f32_32x32x16_bf16 v[2:17], v[114:117], v[110:113], v[2:17]
	s_waitcnt lgkmcnt(0)
	ds_read_b128 v[102:105], v98 offset:49152
	ds_read_b128 v[106:109], v99 offset:32768
	ds_read_b128 v[110:113], v99 offset:36864
	ds_read_b128 v[114:117], v98 offset:53248
	v_mfma_f32_32x32x16_bf16 v[34:49], v[238:241], v[242:245], v[34:49]
	v_mfma_f32_32x32x16_bf16 v[18:33], v[238:241], v[246:249], v[18:33]
	v_mfma_f32_32x32x16_bf16 v[50:65], v[250:253], v[242:245], v[50:65]
	v_mfma_f32_32x32x16_bf16 v[2:17], v[250:253], v[246:249], v[2:17]
	s_waitcnt lgkmcnt(0)
	ds_read_b128 v[238:241], v100 offset:49152
	ds_read_b128 v[242:245], v101 offset:32768
	ds_read_b128 v[246:249], v101 offset:36864
	ds_read_b128 v[250:253], v100 offset:53248
	v_mfma_f32_32x32x16_bf16 v[34:49], v[102:105], v[106:109], v[34:49]
	v_mfma_f32_32x32x16_bf16 v[18:33], v[102:105], v[110:113], v[18:33]
	v_mfma_f32_32x32x16_bf16 v[50:65], v[114:117], v[106:109], v[50:65]
	v_mfma_f32_32x32x16_bf16 v[2:17], v[114:117], v[110:113], v[2:17]
	s_waitcnt vmcnt(0) lgkmcnt(0)
	s_barrier
	ds_read_b128 v[102:105], v74 offset:16384
	ds_read_b128 v[106:109], v96
	ds_read_b128 v[110:113], v96 offset:4096
	ds_read_b128 v[114:117], v74 offset:20480
	v_mfma_f32_32x32x16_bf16 v[34:49], v[238:241], v[242:245], v[34:49]
	v_mfma_f32_32x32x16_bf16 v[18:33], v[238:241], v[246:249], v[18:33]
	v_lshl_add_u64 v[254:255], v[76:77], 0, s[28:29]
	global_load_lds_dwordx4 v[254:255], off
	v_lshl_add_u64 v[254:255], v[78:79], 0, s[28:29]
	s_mov_b32 m0, s87
	s_nop 0
	global_load_lds_dwordx4 v[254:255], off
	v_lshl_add_u64 v[254:255], v[80:81], 0, s[28:29]
	s_mov_b32 m0, s88
	v_mfma_f32_32x32x16_bf16 v[50:65], v[250:253], v[242:245], v[50:65]
	global_load_lds_dwordx4 v[254:255], off
	v_lshl_add_u64 v[254:255], v[82:83], 0, s[28:29]
	s_mov_b32 m0, s89
	s_nop 0
	global_load_lds_dwordx4 v[254:255], off
	v_lshl_add_u64 v[254:255], v[84:85], 0, s[28:29]
	s_mov_b32 m0, s91
	v_mfma_f32_32x32x16_bf16 v[2:17], v[250:253], v[246:249], v[2:17]
	global_load_lds_dwordx4 v[254:255], off
	v_lshl_add_u64 v[254:255], v[86:87], 0, s[28:29]
	s_mov_b32 m0, s92
	s_nop 0
	global_load_lds_dwordx4 v[254:255], off
	v_lshl_add_u64 v[254:255], v[88:89], 0, s[28:29]
	s_mov_b32 m0, s93
	s_nop 0
	global_load_lds_dwordx4 v[254:255], off
	v_lshl_add_u64 v[254:255], v[90:91], 0, s[28:29]
	s_mov_b32 m0, s94
	s_nop 0
	global_load_lds_dwordx4 v[254:255], off
	s_waitcnt lgkmcnt(0)
	ds_read_b128 v[238:241], v95 offset:16384
	ds_read_b128 v[242:245], v97
	ds_read_b128 v[246:249], v97 offset:4096
	ds_read_b128 v[250:253], v95 offset:20480
	v_mfma_f32_32x32x16_bf16 v[34:49], v[102:105], v[106:109], v[34:49]
	s_mov_b32 m0, s1
	v_mfma_f32_32x32x16_bf16 v[18:33], v[102:105], v[110:113], v[18:33]
	v_mfma_f32_32x32x16_bf16 v[50:65], v[114:117], v[106:109], v[50:65]
	v_mfma_f32_32x32x16_bf16 v[2:17], v[114:117], v[110:113], v[2:17]
	s_waitcnt lgkmcnt(0)
	ds_read_b128 v[102:105], v98 offset:16384
	ds_read_b128 v[106:109], v99
	ds_read_b128 v[110:113], v99 offset:4096
	ds_read_b128 v[114:117], v98 offset:20480
	v_mfma_f32_32x32x16_bf16 v[34:49], v[238:241], v[242:245], v[34:49]
	v_mfma_f32_32x32x16_bf16 v[18:33], v[238:241], v[246:249], v[18:33]
	v_mfma_f32_32x32x16_bf16 v[50:65], v[250:253], v[242:245], v[50:65]
	v_mfma_f32_32x32x16_bf16 v[2:17], v[250:253], v[246:249], v[2:17]
	s_waitcnt lgkmcnt(0)
	ds_read_b128 v[238:241], v100 offset:16384
	ds_read_b128 v[242:245], v101
	ds_read_b128 v[246:249], v101 offset:4096
	ds_read_b128 v[250:253], v100 offset:20480
	v_mfma_f32_32x32x16_bf16 v[34:49], v[102:105], v[106:109], v[34:49]
	v_mfma_f32_32x32x16_bf16 v[18:33], v[102:105], v[110:113], v[18:33]
	v_mfma_f32_32x32x16_bf16 v[50:65], v[114:117], v[106:109], v[50:65]
	v_mfma_f32_32x32x16_bf16 v[2:17], v[114:117], v[110:113], v[2:17]
	s_waitcnt vmcnt(0) lgkmcnt(0)
	s_barrier
; template <class Epi>
; DI void gemm_phase(const u16* __restrict__ A, const u16* __restrict__ B, int mtiles, int ntiles, char* lds, const Epi& epi) {
;     ...
;         for (int kt = 0; kt < 16; ++kt) {
;             if (kt + 1 < 16) GSTAGE((kt + 1) & 1, kt + 1, ga, gb);
;             const char* sa = lds + (kt & 1) * 32768; const char* sb = sa + 16384;
; #pragma unroll
;             for (int ks = 0; ks < 4; ++ks) {
;                 bf16x8 fw[2], fx[2];
; #pragma unroll
;                 for (int ct = 0; ct < 2; ++ct) fw[ct] = *(const bf16x8*)(sb + swz(wn * 64 + ct * 32 + r, 2 * ks + h));
; #pragma unroll
;                 for (int tt = 0; tt < 2; ++tt) fx[tt] = *(const bf16x8*)(sa + swz(wm * 64 + tt * 32 + r, 2 * ks + h));
; #pragma unroll
;                 for (int ct = 0; ct < 2; ++ct)
; #pragma unroll
;                     for (int tt = 0; tt < 2; ++tt) acc[ct][tt] = __builtin_amdgcn_mfma_f32_32x32x16_bf16(fw[ct], fx[tt], acc[ct][tt], 0, 0, 0);
;             }
;             __syncthreads();
	ds_read_b128 v[102:105], v74 offset:49152
	ds_read_b128 v[106:109], v96 offset:32768
	ds_read_b128 v[110:113], v96 offset:36864
	ds_read_b128 v[114:117], v74 offset:53248
	v_mfma_f32_32x32x16_bf16 v[34:49], v[238:241], v[242:245], v[34:49]
	v_mfma_f32_32x32x16_bf16 v[18:33], v[238:241], v[246:249], v[18:33]
	v_lshl_add_u64 v[254:255], v[76:77], 0, s[30:31]
	global_load_lds_dwordx4 v[254:255], off
	v_lshl_add_u64 v[254:255], v[78:79], 0, s[30:31]
	s_mov_b32 m0, s7
	s_nop 0
	global_load_lds_dwordx4 v[254:255], off
	v_lshl_add_u64 v[254:255], v[80:81], 0, s[30:31]
	s_mov_b32 m0, s38
	v_mfma_f32_32x32x16_bf16 v[50:65], v[250:253], v[242:245], v[50:65]
	global_load_lds_dwordx4 v[254:255], off
	v_lshl_add_u64 v[254:255], v[82:83], 0, s[30:31]
	s_mov_b32 m0, s39
	s_nop 0
	global_load_lds_dwordx4 v[254:255], off
	v_lshl_add_u64 v[254:255], v[84:85], 0, s[30:31]
	s_mov_b32 m0, s50
	v_mfma_f32_32x32x16_bf16 v[2:17], v[250:253], v[246:249], v[2:17]
	global_load_lds_dwordx4 v[254:255], off
	v_lshl_add_u64 v[254:255], v[86:87], 0, s[30:31]
	s_mov_b32 m0, s51
	s_nop 0
	global_load_lds_dwordx4 v[254:255], off
	v_lshl_add_u64 v[254:255], v[88:89], 0, s[30:31]
	s_mov_b32 m0, s83
	s_nop 0
	global_load_lds_dwordx4 v[254:255], off
	v_lshl_add_u64 v[254:255], v[90:91], 0, s[30:31]
	s_mov_b32 m0, s90
	s_nop 0
	global_load_lds_dwordx4 v[254:255], off
	s_waitcnt lgkmcnt(0)
	ds_read_b128 v[238:241], v95 offset:49152
	ds_read_b128 v[242:245], v97 offset:32768
	ds_read_b128 v[246:249], v97 offset:36864
	ds_read_b128 v[250:253], v95 offset:53248
	v_mfma_f32_32x32x16_bf16 v[34:49], v[102:105], v[106:109], v[34:49]
	s_mov_b32 m0, s86
	v_mfma_f32_32x32x16_bf16 v[18:33], v[102:105], v[110:113], v[18:33]
	v_mfma_f32_32x32x16_bf16 v[50:65], v[114:117], v[106:109], v[50:65]
	v_mfma_f32_32x32x16_bf16 v[2:17], v[114:117], v[110:113], v[2:17]
	s_waitcnt lgkmcnt(0)
	ds_read_b128 v[102:105], v98 offset:49152
	ds_read_b128 v[106:109], v99 offset:32768
	ds_read_b128 v[110:113], v99 offset:36864
	ds_read_b128 v[114:117], v98 offset:53248
	v_mfma_f32_32x32x16_bf16 v[34:49], v[238:241], v[242:245], v[34:49]
	v_mfma_f32_32x32x16_bf16 v[18:33], v[238:241], v[246:249], v[18:33]
	v_mfma_f32_32x32x16_bf16 v[50:65], v[250:253], v[242:245], v[50:65]
	v_mfma_f32_32x32x16_bf16 v[2:17], v[250:253], v[246:249], v[2:17]
	s_waitcnt lgkmcnt(0)
	ds_read_b128 v[238:241], v100 offset:49152
	ds_read_b128 v[242:245], v101 offset:32768
	ds_read_b128 v[246:249], v101 offset:36864
	ds_read_b128 v[250:253], v100 offset:53248
	v_mfma_f32_32x32x16_bf16 v[34:49], v[102:105], v[106:109], v[34:49]
	v_mfma_f32_32x32x16_bf16 v[18:33], v[102:105], v[110:113], v[18:33]
	v_mfma_f32_32x32x16_bf16 v[50:65], v[114:117], v[106:109], v[50:65]
	v_mfma_f32_32x32x16_bf16 v[2:17], v[114:117], v[110:113], v[2:17]
	s_waitcnt vmcnt(0) lgkmcnt(0)
	s_barrier
	ds_read_b128 v[102:105], v74 offset:16384
	ds_read_b128 v[106:109], v96
	ds_read_b128 v[110:113], v96 offset:4096
	ds_read_b128 v[114:117], v74 offset:20480
	v_mfma_f32_32x32x16_bf16 v[34:49], v[238:241], v[242:245], v[34:49]
	v_mfma_f32_32x32x16_bf16 v[18:33], v[238:241], v[246:249], v[18:33]
	v_lshl_add_u64 v[254:255], v[76:77], 0, s[36:37]
	global_load_lds_dwordx4 v[254:255], off
	v_lshl_add_u64 v[254:255], v[78:79], 0, s[36:37]
	s_mov_b32 m0, s87
	s_nop 0
	global_load_lds_dwordx4 v[254:255], off
	v_lshl_add_u64 v[254:255], v[80:81], 0, s[36:37]
	s_mov_b32 m0, s88
	v_mfma_f32_32x32x16_bf16 v[50:65], v[250:253], v[242:245], v[50:65]
	global_load_lds_dwordx4 v[254:255], off
	v_lshl_add_u64 v[254:255], v[82:83], 0, s[36:37]
	s_mov_b32 m0, s89
	s_nop 0
	global_load_lds_dwordx4 v[254:255], off
	v_lshl_add_u64 v[254:255], v[84:85], 0, s[36:37]
	s_mov_b32 m0, s91
	v_mfma_f32_32x32x16_bf16 v[2:17], v[250:253], v[246:249], v[2:17]
	global_load_lds_dwordx4 v[254:255], off
	v_lshl_add_u64 v[254:255], v[86:87], 0, s[36:37]
	s_mov_b32 m0, s92
	s_nop 0
	global_load_lds_dwordx4 v[254:255], off
	v_lshl_add_u64 v[254:255], v[88:89], 0, s[36:37]
	s_mov_b32 m0, s93
	s_nop 0
	global_load_lds_dwordx4 v[254:255], off
	v_lshl_add_u64 v[254:255], v[90:91], 0, s[36:37]
	s_mov_b32 m0, s94
	s_nop 0
	global_load_lds_dwordx4 v[254:255], off
	s_waitcnt lgkmcnt(0)
	ds_read_b128 v[238:241], v95 offset:16384
	ds_read_b128 v[242:245], v97
	ds_read_b128 v[246:249], v97 offset:4096
	ds_read_b128 v[250:253], v95 offset:20480
	v_mfma_f32_32x32x16_bf16 v[34:49], v[102:105], v[106:109], v[34:49]
	s_mov_b32 m0, s1
	v_mfma_f32_32x32x16_bf16 v[18:33], v[102:105], v[110:113], v[18:33]
	v_mfma_f32_32x32x16_bf16 v[50:65], v[114:117], v[106:109], v[50:65]
	v_mfma_f32_32x32x16_bf16 v[2:17], v[114:117], v[110:113], v[2:17]
	s_waitcnt lgkmcnt(0)
	ds_read_b128 v[102:105], v98 offset:16384
	ds_read_b128 v[106:109], v99
	ds_read_b128 v[110:113], v99 offset:4096
	ds_read_b128 v[114:117], v98 offset:20480
	v_mfma_f32_32x32x16_bf16 v[34:49], v[238:241], v[242:245], v[34:49]
	v_mfma_f32_32x32x16_bf16 v[18:33], v[238:241], v[246:249], v[18:33]
	v_mfma_f32_32x32x16_bf16 v[50:65], v[250:253], v[242:245], v[50:65]
	v_mfma_f32_32x32x16_bf16 v[2:17], v[250:253], v[246:249], v[2:17]
	s_waitcnt lgkmcnt(0)
	ds_read_b128 v[238:241], v100 offset:16384
	ds_read_b128 v[242:245], v101
	ds_read_b128 v[246:249], v101 offset:4096
	ds_read_b128 v[250:253], v100 offset:20480
	v_mfma_f32_32x32x16_bf16 v[34:49], v[102:105], v[106:109], v[34:49]
	v_mfma_f32_32x32x16_bf16 v[18:33], v[102:105], v[110:113], v[18:33]
	v_mfma_f32_32x32x16_bf16 v[50:65], v[114:117], v[106:109], v[50:65]
	v_mfma_f32_32x32x16_bf16 v[2:17], v[114:117], v[110:113], v[2:17]
	s_waitcnt vmcnt(0) lgkmcnt(0)
	s_barrier
; template <class Epi>
; DI void gemm_phase(const u16* __restrict__ A, const u16* __restrict__ B, int mtiles, int ntiles, char* lds, const Epi& epi) {
;     ...
;         for (int kt = 0; kt < 16; ++kt) {
;             if (kt + 1 < 16) GSTAGE((kt + 1) & 1, kt + 1, ga, gb);
;             const char* sa = lds + (kt & 1) * 32768; const char* sb = sa + 16384;
; #pragma unroll
;             for (int ks = 0; ks < 4; ++ks) {
;                 bf16x8 fw[2], fx[2];
; #pragma unroll
;                 for (int ct = 0; ct < 2; ++ct) fw[ct] = *(const bf16x8*)(sb + swz(wn * 64 + ct * 32 + r, 2 * ks + h));
; #pragma unroll
;                 for (int tt = 0; tt < 2; ++tt) fx[tt] = *(const bf16x8*)(sa + swz(wm * 64 + tt * 32 + r, 2 * ks + h));
; #pragma unroll
;                 for (int ct = 0; ct < 2; ++ct)
; #pragma unroll
;                     for (int tt = 0; tt < 2; ++tt) acc[ct][tt] = __builtin_amdgcn_mfma_f32_32x32x16_bf16(fw[ct], fx[tt], acc[ct][tt], 0, 0, 0);
;             }
;             __syncthreads();
	ds_read_b128 v[102:105], v74 offset:49152
	ds_read_b128 v[106:109], v96 offset:32768
	ds_read_b128 v[110:113], v96 offset:36864
	ds_read_b128 v[114:117], v74 offset:53248
	v_mfma_f32_32x32x16_bf16 v[34:49], v[238:241], v[242:245], v[34:49]
	v_mfma_f32_32x32x16_bf16 v[18:33], v[238:241], v[246:249], v[18:33]
	v_lshl_add_u64 v[254:255], v[76:77], 0, s[68:69]
	global_load_lds_dwordx4 v[254:255], off
	v_lshl_add_u64 v[254:255], v[78:79], 0, s[68:69]
	s_mov_b32 m0, s7
	v_lshl_add_u64 v[76:77], v[76:77], 0, s[70:71]
	global_load_lds_dwordx4 v[254:255], off
	v_lshl_add_u64 v[254:255], v[80:81], 0, s[68:69]
	s_mov_b32 m0, s38
	v_mfma_f32_32x32x16_bf16 v[50:65], v[250:253], v[242:245], v[50:65]
	global_load_lds_dwordx4 v[254:255], off
	v_lshl_add_u64 v[254:255], v[82:83], 0, s[68:69]
	s_mov_b32 m0, s39
	s_nop 0
	global_load_lds_dwordx4 v[254:255], off
	v_lshl_add_u64 v[254:255], v[84:85], 0, s[68:69]
	s_mov_b32 m0, s50
	v_mfma_f32_32x32x16_bf16 v[2:17], v[250:253], v[246:249], v[2:17]
	global_load_lds_dwordx4 v[254:255], off
	v_lshl_add_u64 v[254:255], v[86:87], 0, s[68:69]
	s_mov_b32 m0, s51
	s_nop 0
	global_load_lds_dwordx4 v[254:255], off
	v_lshl_add_u64 v[254:255], v[88:89], 0, s[68:69]
	s_mov_b32 m0, s83
	s_nop 0
	global_load_lds_dwordx4 v[254:255], off
	v_lshl_add_u64 v[254:255], v[90:91], 0, s[68:69]
	s_mov_b32 m0, s90
	s_nop 0
	global_load_lds_dwordx4 v[254:255], off
	s_waitcnt lgkmcnt(0)
	ds_read_b128 v[238:241], v95 offset:49152
	ds_read_b128 v[242:245], v97 offset:32768
	ds_read_b128 v[246:249], v97 offset:36864
	ds_read_b128 v[250:253], v95 offset:53248
	v_mfma_f32_32x32x16_bf16 v[34:49], v[102:105], v[106:109], v[34:49]
	s_mov_b32 m0, s86
	s_mov_b32 s86, 0
	v_mfma_f32_32x32x16_bf16 v[18:33], v[102:105], v[110:113], v[18:33]
	v_mfma_f32_32x32x16_bf16 v[50:65], v[114:117], v[106:109], v[50:65]
	v_mfma_f32_32x32x16_bf16 v[2:17], v[114:117], v[110:113], v[2:17]
	s_waitcnt lgkmcnt(0)
	ds_read_b128 v[102:105], v98 offset:49152
	ds_read_b128 v[106:109], v99 offset:32768
	ds_read_b128 v[110:113], v99 offset:36864
	ds_read_b128 v[114:117], v98 offset:53248
	v_mfma_f32_32x32x16_bf16 v[34:49], v[238:241], v[242:245], v[34:49]
	v_mfma_f32_32x32x16_bf16 v[18:33], v[238:241], v[246:249], v[18:33]
	v_mfma_f32_32x32x16_bf16 v[50:65], v[250:253], v[242:245], v[50:65]
	v_mfma_f32_32x32x16_bf16 v[2:17], v[250:253], v[246:249], v[2:17]
	s_waitcnt lgkmcnt(0)
	ds_read_b128 v[238:241], v100 offset:49152
	ds_read_b128 v[242:245], v101 offset:32768
	ds_read_b128 v[246:249], v101 offset:36864
	ds_read_b128 v[250:253], v100 offset:53248
	v_mfma_f32_32x32x16_bf16 v[34:49], v[102:105], v[106:109], v[34:49]
	v_mfma_f32_32x32x16_bf16 v[18:33], v[102:105], v[110:113], v[18:33]
	v_mfma_f32_32x32x16_bf16 v[50:65], v[114:117], v[106:109], v[50:65]
	v_mfma_f32_32x32x16_bf16 v[2:17], v[114:117], v[110:113], v[2:17]
	s_waitcnt vmcnt(0) lgkmcnt(0)
	s_barrier
	global_load_lds_dwordx4 v[76:77], off
	v_lshl_add_u64 v[76:77], v[78:79], 0, s[70:71]
	s_mov_b32 m0, s87
	v_mfma_f32_32x32x16_bf16 v[34:49], v[238:241], v[242:245], v[34:49]
	global_load_lds_dwordx4 v[76:77], off
	v_lshl_add_u64 v[76:77], v[80:81], 0, s[70:71]
	s_mov_b32 m0, s88
	s_mov_b32 s88, 0
	global_load_lds_dwordx4 v[76:77], off
	v_lshl_add_u64 v[76:77], v[82:83], 0, s[70:71]
	s_mov_b32 m0, s89
	v_mfma_f32_32x32x16_bf16 v[18:33], v[238:241], v[246:249], v[18:33]
	global_load_lds_dwordx4 v[76:77], off
	v_lshl_add_u64 v[76:77], v[84:85], 0, s[70:71]
	s_mov_b32 m0, s91
	s_nop 0
	global_load_lds_dwordx4 v[76:77], off
	v_lshl_add_u64 v[76:77], v[86:87], 0, s[70:71]
	s_mov_b32 m0, s92
	v_mfma_f32_32x32x16_bf16 v[50:65], v[250:253], v[242:245], v[50:65]
	global_load_lds_dwordx4 v[76:77], off
	v_lshl_add_u64 v[76:77], v[88:89], 0, s[70:71]
	s_mov_b32 m0, s93
	s_nop 0
	global_load_lds_dwordx4 v[76:77], off
	v_lshl_add_u64 v[76:77], v[90:91], 0, s[70:71]
	s_mov_b32 m0, s94
	v_mfma_f32_32x32x16_bf16 v[2:17], v[250:253], v[246:249], v[2:17]
	global_load_lds_dwordx4 v[76:77], off
	ds_read_b128 v[76:79], v74 offset:16384
	ds_read_b128 v[80:83], v96
	ds_read_b128 v[84:87], v96 offset:4096
	ds_read_b128 v[88:91], v74 offset:20480
	s_waitcnt lgkmcnt(0)
	v_mfma_f32_32x32x16_bf16 v[34:49], v[76:79], v[80:83], v[34:49]
	v_mfma_f32_32x32x16_bf16 v[18:33], v[76:79], v[84:87], v[18:33]
	v_mfma_f32_32x32x16_bf16 v[50:65], v[88:91], v[80:83], v[50:65]
	v_mfma_f32_32x32x16_bf16 v[2:17], v[88:91], v[84:87], v[2:17]
	ds_read_b128 v[76:79], v95 offset:16384
	ds_read_b128 v[80:83], v97
	ds_read_b128 v[84:87], v97 offset:4096
	ds_read_b128 v[88:91], v95 offset:20480
	s_waitcnt lgkmcnt(0)
	v_mfma_f32_32x32x16_bf16 v[34:49], v[76:79], v[80:83], v[34:49]
	v_mfma_f32_32x32x16_bf16 v[18:33], v[76:79], v[84:87], v[18:33]
	v_mfma_f32_32x32x16_bf16 v[50:65], v[88:91], v[80:83], v[50:65]
	v_mfma_f32_32x32x16_bf16 v[2:17], v[88:91], v[84:87], v[2:17]
	ds_read_b128 v[76:79], v98 offset:16384
	ds_read_b128 v[80:83], v99
	ds_read_b128 v[84:87], v99 offset:4096
	ds_read_b128 v[88:91], v98 offset:20480
	s_waitcnt lgkmcnt(0)
	v_mfma_f32_32x32x16_bf16 v[34:49], v[76:79], v[80:83], v[34:49]
	v_mfma_f32_32x32x16_bf16 v[18:33], v[76:79], v[84:87], v[18:33]
	v_mfma_f32_32x32x16_bf16 v[50:65], v[88:91], v[80:83], v[50:65]
	v_mfma_f32_32x32x16_bf16 v[2:17], v[88:91], v[84:87], v[2:17]
	ds_read_b128 v[76:79], v100 offset:16384
	ds_read_b128 v[80:83], v101
	ds_read_b128 v[84:87], v101 offset:4096
	ds_read_b128 v[88:91], v100 offset:20480
	s_waitcnt vmcnt(0) lgkmcnt(0)
	s_barrier
; #define TILE_MN(t, M0, N0) do { int pan_ = (t) / (mtiles * 8); if (pan_ >= npan) pan_ = npan - 1; const int pw_ = (pan_ == npan - 1) ? ntiles - 8 * pan_ : 8; const int loc_ = (t) - pan_ * mtiles * 8; \
;         M0 = (loc_ / pw_) * 128; N0 = (8 * pan_ + loc_ % pw_) * 128; } while (0)
; template <class Epi>
; DI void gemm_phase(const u16* __restrict__ A, const u16* __restrict__ B, int mtiles, int ntiles, char* lds, const Epi& epi) {
;     ...
;         for (int kt = 0; kt < 16; ++kt) {
;             if (kt + 1 < 16) GSTAGE((kt + 1) & 1, kt + 1, ga, gb);
;             const char* sa = lds + (kt & 1) * 32768; const char* sb = sa + 16384;
; #pragma unroll
;             for (int ks = 0; ks < 4; ++ks) {
;                 bf16x8 fw[2], fx[2];
; #pragma unroll
;                 for (int ct = 0; ct < 2; ++ct) fw[ct] = *(const bf16x8*)(sb + swz(wn * 64 + ct * 32 + r, 2 * ks + h));
; #pragma unroll
;                 for (int tt = 0; tt < 2; ++tt) fx[tt] = *(const bf16x8*)(sa + swz(wm * 64 + tt * 32 + r, 2 * ks + h));
; #pragma unroll
;                 for (int ct = 0; ct < 2; ++ct)
; #pragma unroll
;                     for (int tt = 0; tt < 2; ++tt) acc[ct][tt] = __builtin_amdgcn_mfma_f32_32x32x16_bf16(fw[ct], fx[tt], acc[ct][tt], 0, 0, 0);
;             }
;             __syncthreads();
;         }
;         const int nxt = tile + (int)gridDim.x; int m1 = 0, n1 = 0;
;         if (nxt < ntile) { TILE_MN(nxt, m1, n1); GSTAGE(0, 0, A + (size_t)m1 * 1024, B + (size_t)n1 * 1024); }
	v_mfma_f32_32x32x16_bf16 v[34:49], v[76:79], v[80:83], v[34:49]
	v_mfma_f32_32x32x16_bf16 v[18:33], v[76:79], v[84:87], v[18:33]
	v_mfma_f32_32x32x16_bf16 v[50:65], v[88:91], v[80:83], v[50:65]
	v_mfma_f32_32x32x16_bf16 v[2:17], v[88:91], v[84:87], v[2:17]
	ds_read_b128 v[76:79], v96 offset:32768
	ds_read_b128 v[80:83], v96 offset:36864
	ds_read_b128 v[84:87], v74 offset:49152
	ds_read_b128 v[88:91], v74 offset:53248
	s_waitcnt lgkmcnt(1)
	v_mfma_f32_32x32x16_bf16 v[34:49], v[84:87], v[76:79], v[34:49]
	v_mfma_f32_32x32x16_bf16 v[18:33], v[84:87], v[80:83], v[18:33]
	s_waitcnt lgkmcnt(0)
	v_mfma_f32_32x32x16_bf16 v[50:65], v[88:91], v[76:79], v[50:65]
	v_mfma_f32_32x32x16_bf16 v[2:17], v[88:91], v[80:83], v[2:17]
	ds_read_b128 v[76:79], v95 offset:49152
	ds_read_b128 v[80:83], v97 offset:32768
	ds_read_b128 v[84:87], v97 offset:36864
	ds_read_b128 v[88:91], v95 offset:53248
	s_waitcnt lgkmcnt(2)
	v_mfma_f32_32x32x16_bf16 v[34:49], v[76:79], v[80:83], v[34:49]
	s_waitcnt lgkmcnt(1)
	v_mfma_f32_32x32x16_bf16 v[18:33], v[76:79], v[84:87], v[18:33]
	s_waitcnt lgkmcnt(0)
	v_mfma_f32_32x32x16_bf16 v[50:65], v[88:91], v[80:83], v[50:65]
	v_mfma_f32_32x32x16_bf16 v[2:17], v[88:91], v[84:87], v[2:17]
	ds_read_b128 v[76:79], v98 offset:49152
	ds_read_b128 v[80:83], v99 offset:32768
	ds_read_b128 v[84:87], v99 offset:36864
	ds_read_b128 v[88:91], v98 offset:53248
	s_waitcnt lgkmcnt(2)
	v_mfma_f32_32x32x16_bf16 v[34:49], v[76:79], v[80:83], v[34:49]
	s_waitcnt lgkmcnt(1)
	v_mfma_f32_32x32x16_bf16 v[18:33], v[76:79], v[84:87], v[18:33]
	s_waitcnt lgkmcnt(0)
	v_mfma_f32_32x32x16_bf16 v[50:65], v[88:91], v[80:83], v[50:65]
	v_mfma_f32_32x32x16_bf16 v[2:17], v[88:91], v[84:87], v[2:17]
	ds_read_b128 v[76:79], v100 offset:49152
	ds_read_b128 v[80:83], v101 offset:32768
	ds_read_b128 v[84:87], v101 offset:36864
	ds_read_b128 v[88:91], v100 offset:53248
	s_waitcnt lgkmcnt(0)
	s_barrier
	v_mfma_f32_32x32x16_bf16 v[34:49], v[76:79], v[80:83], v[34:49]
	v_mfma_f32_32x32x16_bf16 v[18:33], v[76:79], v[84:87], v[18:33]
	v_mfma_f32_32x32x16_bf16 v[50:65], v[88:91], v[80:83], v[50:65]
	v_mfma_f32_32x32x16_bf16 v[2:17], v[88:91], v[84:87], v[2:17]
	s_cbranch_scc1 .LBB0_99
	s_mov_b32 m0, s1
	s_mul_hi_i32 s1, s33, 0x3e0f83e1
	s_lshr_b32 s86, s1, 31
	s_ashr_i32 s1, s1, 8
	s_add_i32 s1, s1, s86
	s_cmpk_lt_i32 s33, 0x1080
	s_cselect_b32 s1, s1, 3
	s_cmp_eq_u32 s1, 3
	s_cselect_b32 s87, 9, 8
	v_cvt_f32_ubyte0_e32 v74, s87
	v_rcp_iflag_f32_e32 v74, v74
	s_sub_i32 s91, 0, s87
	s_mul_i32 s86, s1, 0xfffffbe0
	s_add_i32 s88, s33, s86
	v_mul_f32_e32 v74, 0x4f7ffffe, v74
	v_cvt_u32_f32_e32 v74, v74
	s_abs_i32 s89, s88
	s_ashr_i32 s86, s88, 31
	v_readfirstlane_b32 s92, v74
	s_mul_i32 s91, s91, s92
	s_mul_hi_u32 s91, s92, s91
	s_add_i32 s92, s92, s91
	s_mul_hi_u32 s91, s89, s92
	s_mul_i32 s92, s91, s87
	s_sub_i32 s89, s89, s92
	s_add_i32 s92, s91, 1
	s_sub_i32 s93, s89, s87
	s_cmp_ge_u32 s89, s87
	s_cselect_b32 s91, s92, s91
	s_cselect_b32 s89, s93, s89
	s_add_i32 s92, s91, 1
	s_cmp_ge_u32 s89, s87
	s_cselect_b32 s89, s92, s91
	s_xor_b32 s89, s89, s86
	s_sub_i32 s89, s89, s86
	s_lshl_b32 s86, s89, 7
	s_mul_i32 s89, s89, s87
	s_sub_i32 s87, s88, s89
	s_lshl_b32 s1, s1, 10
	s_lshl_b32 s87, s87, 7
	s_add_i32 s88, s87, s1
	s_ashr_i32 s87, s86, 31
	s_lshl_b64 s[92:93], s[86:87], 11
	s_add_u32 s92, s54, s92
	s_addc_u32 s93, s55, s93
	s_ashr_i32 s89, s88, 31
	s_lshl_b64 s[94:95], s[88:89], 11
	v_readlane_b32 s1, v236, 9
	s_add_u32 s94, s1, s94
	v_readlane_b32 s1, v236, 11
	s_addc_u32 s95, s1, s95
	v_lshl_add_u64 v[76:77], s[92:93], 0, v[66:67]
	global_load_lds_dwordx4 v[76:77], off
	v_lshl_add_u64 v[66:67], s[94:95], 0, v[66:67]
	s_mov_b32 m0, s7
	s_nop 0
	global_load_lds_dwordx4 v[66:67], off
	v_lshl_add_u64 v[66:67], s[92:93], 0, v[68:69]
	s_mov_b32 m0, s38
	s_nop 0
	global_load_lds_dwordx4 v[66:67], off
	v_lshl_add_u64 v[66:67], s[94:95], 0, v[68:69]
	s_mov_b32 m0, s39
	s_nop 0
	global_load_lds_dwordx4 v[66:67], off
	v_lshl_add_u64 v[66:67], s[92:93], 0, v[70:71]
	s_mov_b32 m0, s50
	s_nop 0
	global_load_lds_dwordx4 v[66:67], off
	v_lshl_add_u64 v[66:67], s[94:95], 0, v[70:71]
	s_mov_b32 m0, s51
	s_nop 0
	global_load_lds_dwordx4 v[66:67], off
	v_lshl_add_u64 v[66:67], s[92:93], 0, v[72:73]
	s_mov_b32 m0, s83
	s_nop 0
	global_load_lds_dwordx4 v[66:67], off
	v_lshl_add_u64 v[66:67], s[94:95], 0, v[72:73]
	s_mov_b32 m0, s90
	s_nop 0
	global_load_lds_dwordx4 v[66:67], off

; DI void phase_rwkv_out(const Params& p, char* lds) {
;     ...
;     for (int wu = gw; wu < 8192 + 256; wu += nw) {
;         int u, tg, b, h, c = 0, row0; bool prm = wu < 8192;
;         if (prm) { u = wu >> 2; tg = wu & 3; b = u >> 10; h = (u >> 7) & 7; c = u & 127; row0 = b * 8192 + c * 64; }
;         else { const int s = wu - 8192; u = 2048 + s; tg = 0; b = s >> 3; h = s & 7; row0 = NTP + b * 16; }
;         const int t = 16 * tg + i16; const int row = row0 + t;
;         u16* z = (u16*)(p.ws + W_XB) + (size_t)row * DM + 512 + h * 64;
;         const u16* qt = QT + (size_t)u * 4096 + t * 64 + 8 * g; const bf16x8 bq0 = *(const bf16x8*)qt, bq1 = *(const bf16x8*)(qt + 32);
;         { const float a_ = p.mix[1024 + h * 64 + lane], b_ = p.gn_g[h * 64 + lane], c_ = p.gn_b[h * 64 + lane];
;             asm volatile("s_waitcnt lgkmcnt(0)" ::: "memory"); pw[lane] = a_; pw[64 + lane] = b_; pw[128 + lane] = c_; asm volatile("s_waitcnt lgkmcnt(0)" ::: "memory"); }
;         const int wofs = 16 * (g & 1) + 8 * (g >> 1);
;         const int mode = t > 0 ? 0 : (prm ? (c > 0 ? 0 : 1) : 2);
;         uint2 ylw[4], cvw[4], grw[4], pvw[4];
;         { const u16* pr_ = proj + (size_t)row * NC + h * 64 + wofs; const u16* pp_ = proj + (size_t)(mode == 0 ? row - 1 : row) * NC + C_RV + h * 64 + wofs;
; #pragma unroll
;             for (int mp = 0; mp < 2; ++mp) {
;                 unwiden16(*(const uint4*)(z + 32 * mp + wofs), ylw[2 * mp], ylw[2 * mp + 1]);
;                 unwiden16(*(const uint4*)(pr_ + C_RV + 32 * mp), cvw[2 * mp], cvw[2 * mp + 1]);
;                 unwiden16(*(const uint4*)(pr_ + C_GR + 32 * mp), grw[2 * mp], grw[2 * mp + 1]);
;                 unwiden16(*(const uint4*)(pp_ + 32 * mp), pvw[2 * mp], pvw[2 * mp + 1]); } }
.LBB0_495:
	v_cmp_lt_i32_e32 vcc, s21, v1
	s_and_saveexec_b64 s[0:1], vcc
	s_xor_b64 s[0:1], exec, s[0:1]
	v_add_u32_e32 v2, 0xffffe000, v1
	v_lshrrev_b32_e32 v36, 3, v2
	v_add_u32_e32 v18, 0xffffe800, v1
	v_lshl_add_u32 v2, v36, 4, v107
	s_or_saveexec_b64 s[0:1], s[0:1]
	v_mov_b32_e32 v4, 0
	v_mov_b32_e32 v3, 2
	v_mov_b32_e32 v5, v1
	s_xor_b64 exec, exec, s[0:1]
	v_ashrrev_i32_e32 v18, 2, v1
	v_ashrrev_i32_e32 v36, 12, v1
	v_and_b32_e32 v3, 0x7f, v18
	v_lshlrev_b32_e32 v2, 13, v36
	v_cmp_eq_u32_e32 vcc, 0, v3
	v_lshrrev_b32_e32 v5, 9, v1
	v_lshl_or_b32 v2, v3, 6, v2
	v_and_b32_e32 v4, 48, v105
	v_cndmask_b32_e64 v3, 0, 1, vcc
	s_or_b64 exec, exec, s[0:1]
	v_lshlrev_b32_e32 v5, 6, v5
	v_and_b32_e32 v81, 0x1c0, v5
	v_or_b32_e32 v5, v81, v218
	v_lshlrev_b32_e32 v6, 2, v5
	v_mov_b32_e32 v7, v221
	v_lshl_add_u64 v[8:9], s[78:79], 0, v[6:7]
	v_add_co_u32_e32 v8, vcc, s22, v8
	v_or_b32_e32 v37, v4, v223
	s_nop 0
	v_addc_co_u32_e32 v9, vcc, 0, v9, vcc
	global_load_dword v172, v6, s[46:47]
	global_load_dword v173, v6, s[48:49]
	global_load_dword v174, v[8:9], off
	v_ashrrev_i32_e32 v19, 31, v18
	v_cmp_eq_u32_e32 vcc, 0, v37
	v_add_u32_e32 v2, v37, v2
	v_lshlrev_b64 v[38:39], 13, v[18:19]
	v_cndmask_b32_e32 v119, 0, v3, vcc
	v_mov_b32_e32 v5, v221
	v_lshlrev_b32_e32 v4, 7, v37
	v_lshlrev_b32_e32 v220, 1, v81
	v_lshl_add_u64 v[6:7], s[6:7], 0, v[38:39]
	v_mad_i64_i32 v[8:9], s[0:1], v2, s18, v[74:75]
	v_cmp_eq_u32_e32 vcc, 0, v119
	v_lshl_add_u64 v[4:5], v[6:7], 0, v[4:5]
	v_lshl_add_u64 v[6:7], v[8:9], 0, v[220:221]
	v_subbrev_co_u32_e32 v13, vcc, 0, v2, vcc
	v_ashrrev_i32_e32 v3, 31, v2
	v_mad_i64_i32 v[8:9], s[0:1], v13, s18, v[74:75]
	v_lshl_add_u64 v[6:7], v[6:7], 0, v[76:77]
	v_lshlrev_b64 v[2:3], 11, v[2:3]
	v_lshl_add_u64 v[8:9], v[8:9], 0, v[220:221]
	v_add_co_u32_e32 v34, vcc, s22, v6
	v_lshl_add_u64 v[2:3], s[54:55], 0, v[2:3]
	v_lshl_add_u64 v[4:5], v[4:5], 0, v[72:73]
	v_lshl_add_u64 v[32:33], v[8:9], 0, v[76:77]
	v_addc_co_u32_e32 v35, vcc, 0, v7, vcc
	v_lshl_add_u64 v[84:85], v[2:3], 0, v[220:221]
	global_load_dwordx4 v[28:31], v[4:5], off
	global_load_dwordx4 v[24:27], v[4:5], off offset:64
	s_waitcnt lgkmcnt(0)
	v_add_co_u32_e32 v50, vcc, s22, v32
	v_lshl_add_u64 v[48:49], v[84:85], 0, v[76:77]
	s_nop 0
	v_addc_co_u32_e32 v51, vcc, 0, v33, vcc
	v_lshl_add_u64 v[32:33], v[32:33], 0, s[10:11]
	v_lshl_add_u64 v[38:39], v[70:71], 0, v[38:39]
	v_add_co_u32_e32 v68, vcc, s22, v38
	v_lshlrev_b64 v[18:19], 8, v[18:19]
	s_nop 0
	v_addc_co_u32_e32 v69, vcc, 0, v39, vcc
	v_lshl_add_u64 v[18:19], s[8:9], 0, v[18:19]
	v_lshlrev_b32_e32 v220, 2, v37
	v_lshl_add_u64 v[18:19], v[18:19], 0, v[220:221]
	v_cmp_ne_u32_e32 vcc, 0, v119
	v_cmp_ne_u32_e64 s[0:1], 1, v119
	global_load_dwordx4 v[40:43], v[48:49], off offset:1024
	global_load_dwordx4 v[2:5], v[34:35], off offset:2048
	global_load_dwordx4 v[6:9], v[34:35], off offset:3328
	global_load_dwordx4 v[20:23], v[50:51], off offset:2048
	global_load_dwordx4 v[44:47], v[48:49], off offset:1088
	global_load_dwordx4 v[10:13], v[34:35], off offset:2112
	global_load_dwordx4 v[14:17], v[34:35], off offset:3392
	global_load_dwordx4 v[32:35], v[32:33], off offset:64
	s_nop 0
	global_load_dwordx4 v[48:51], v[38:39], off
	global_load_dwordx4 v[52:55], v[38:39], off offset:2048
	global_load_dwordx4 v[56:59], v[68:69], off
	global_load_dwordx4 v[60:63], v[68:69], off offset:2048
	global_load_dwordx4 v[64:67], v[38:39], off offset:64
	global_load_dwordx4 v[88:91], v[38:39], off offset:2112
	global_load_dwordx4 v[92:95], v[68:69], off offset:64
	global_load_dwordx4 v[96:99], v[68:69], off offset:2112
	global_load_dword v86, v[18:19], off
	s_waitcnt vmcnt(20)
	ds_write_b32 v87, v173 offset:512
	s_waitcnt vmcnt(19)
	ds_write2st64_b32 v87, v174, v172 offset1:1
	s_waitcnt lgkmcnt(0)
	s_waitcnt vmcnt(16)
	v_mov_b32_e32 v37, v42
	s_nop 1
	v_permlane16_swap_b32_e32 v40, v37
	v_permlane16_swap_b32_e32 v41, v43
	s_waitcnt vmcnt(15)
	v_mov_b32_e32 v112, v4
	v_mov_b32_e32 v111, v5
	s_waitcnt vmcnt(12)
	v_mov_b32_e32 v4, v46
	v_mov_b32_e32 v5, v47
	s_waitcnt vmcnt(10)
	v_mov_b32_e32 v108, v16
	v_mov_b32_e32 v83, v17
	v_lshlrev_b32_e32 v16, 16, v40
	v_and_b32_e32 v17, 0xffff0000, v40
	v_lshlrev_b32_e32 v18, 16, v41
	v_and_b32_e32 v19, 0xffff0000, v41
	v_permlane16_swap_b32_e32 v44, v4
	v_permlane16_swap_b32_e32 v45, v5
	v_lshlrev_b32_e32 v40, 16, v37
	v_and_b32_e32 v41, 0xffff0000, v37
	v_lshlrev_b32_e32 v42, 16, v43
	s_waitcnt vmcnt(8)
	v_mfma_f32_16x16x32_bf16 v[16:19], v[48:51], v[28:31], v[16:19]
	v_and_b32_e32 v43, 0xffff0000, v43
	v_lshlrev_b32_e32 v46, 16, v44
	v_and_b32_e32 v47, 0xffff0000, v44
	s_waitcnt vmcnt(7)
; DI float bflo(unsigned u) { return __uint_as_float(u << 16); }
; DI float bfhi(unsigned u) { return __uint_as_float(u & 0xffff0000u); }
; DI float xadd16(float v) { const unsigned x = __float_as_uint(v); auto r = __builtin_amdgcn_permlane16_swap(x, x, false, false); return __uint_as_float(r[0]) + __uint_as_float(r[1]); }
; DI float xadd32(float v) { const unsigned x = __float_as_uint(v); auto r = __builtin_amdgcn_permlane32_swap(x, x, false, false); return __uint_as_float(r[0]) + __uint_as_float(r[1]); }
; DI void phase_rwkv_out(const Params& p, char* lds) {
;     ...
;                 unwiden16(*(const uint4*)(z + 32 * mp + wofs), ylw[2 * mp], ylw[2 * mp + 1]);
;                 unwiden16(*(const uint4*)(pr_ + C_RV + 32 * mp), cvw[2 * mp], cvw[2 * mp + 1]);
;                 unwiden16(*(const uint4*)(pr_ + C_GR + 32 * mp), grw[2 * mp], grw[2 * mp + 1]);
;                 unwiden16(*(const uint4*)(pp_ + 32 * mp), pvw[2 * mp], pvw[2 * mp + 1]); } }
;         f32x4 y[4];
; #pragma unroll
;         for (int mt = 0; mt < 4; ++mt) {
;             const uint2 yl = ylw[mt]; f32x4 a = {bflo(yl.x), bfhi(yl.x), bflo(yl.y), bfhi(yl.y)};
;             const u16* sp = SST + (size_t)u * 4096 + (16 * mt + i16) * 64 + 8 * g;
;             a = __builtin_amdgcn_mfma_f32_16x16x32_bf16(*(const bf16x8*)sp, bq0, a, 0, 0, 0); a = __builtin_amdgcn_mfma_f32_16x16x32_bf16(*(const bf16x8*)(sp + 32), bq1, a, 0, 0, 0);
;             y[mt] = a;
;         }
;         float s1 = 0.f;
; #pragma unroll
;         for (int mt = 0; mt < 4; ++mt) s1 += (y[mt][0] + y[mt][1]) + (y[mt][2] + y[mt][3]);
;         s1 = xadd16(s1); s1 = xadd32(s1);
;         const float mu = s1 * (1.f / 64.f); float s2 = 0.f;
; #pragma unroll
;         for (int mt = 0; mt < 4; ++mt)
; #pragma unroll
;             for (int e = 0; e < 4; ++e) { const float d = y[mt][e] - mu; s2 += d * d; }
;         s2 = xadd16(s2); s2 = xadd32(s2);
;         const float rs = __builtin_amdgcn_rsqf(s2 * (1.f / 64.f) + 64e-5f);
	v_mfma_f32_16x16x32_bf16 v[40:43], v[52:55], v[28:31], v[40:43]
	v_lshlrev_b32_e32 v48, 16, v45
	v_and_b32_e32 v49, 0xffff0000, v45
	v_lshlrev_b32_e32 v44, 16, v4
	v_and_b32_e32 v45, 0xffff0000, v4
	s_waitcnt vmcnt(6)
	v_mfma_f32_16x16x32_bf16 v[48:51], v[56:59], v[28:31], v[46:49]
	v_mov_b32_e32 v38, v22
	v_mov_b32_e32 v39, v23
	v_mov_b32_e32 v110, v8
	v_lshlrev_b32_e32 v46, 16, v5
	v_and_b32_e32 v47, 0xffff0000, v5
	s_waitcnt vmcnt(4)
	v_mfma_f32_16x16x32_bf16 v[16:19], v[64:67], v[24:27], v[16:19]
	v_mov_b32_e32 v109, v9
	v_mov_b32_e32 v114, v12
	v_mov_b32_e32 v113, v13
	v_mfma_f32_16x16x32_bf16 v[28:31], v[60:63], v[28:31], v[44:47]
	v_mov_b32_e32 v115, v34
	s_nop 2
	v_add_f32_e32 v4, v16, v17
	v_add_f32_e32 v5, v18, v19
	s_waitcnt vmcnt(3)
	v_mfma_f32_16x16x32_bf16 v[40:43], v[88:91], v[24:27], v[40:43]
	v_add_f32_e32 v4, v4, v5
	v_add_f32_e32 v4, 0, v4
	v_mov_b32_e32 v116, v35
	s_waitcnt vmcnt(2)
	v_mfma_f32_16x16x32_bf16 v[44:47], v[92:95], v[24:27], v[48:51]
	v_permlane16_swap_b32_e32 v2, v112
	s_nop 1
	v_add_f32_e32 v8, v40, v41
	s_waitcnt vmcnt(1)
	v_mfma_f32_16x16x32_bf16 v[22:25], v[96:99], v[24:27], v[28:31]
	v_add_f32_e32 v9, v42, v43
	s_nop 0
	v_add_f32_e32 v12, v44, v45
	v_add_f32_e32 v13, v46, v47
	v_add_f32_e32 v5, v8, v9
	v_add_f32_e32 v8, v12, v13
	s_nop 1
	v_add_f32_e32 v26, v22, v23
	v_add_f32_e32 v27, v24, v25
	v_add_f32_e32 v4, v4, v5
	v_add_f32_e32 v9, v26, v27
	v_add_f32_e32 v4, v4, v8
	v_add_f32_e32 v4, v4, v9
	v_mov_b32_e32 v5, v4
	s_nop 1
	v_permlane16_swap_b32_e32 v4, v5
	v_add_f32_e32 v4, v4, v5
	v_mov_b32_e32 v5, v4
	s_nop 1
	v_permlane32_swap_b32_e32 v4, v5
	v_add_f32_e32 v4, v4, v5
	v_mul_f32_e32 v8, 0x3c800000, v4
	v_pk_add_f32 v[90:91], v[16:17], v[8:9] op_sel_hi:[1,0] neg_lo:[0,1] neg_hi:[0,1]
	v_pk_add_f32 v[88:89], v[18:19], v[8:9] op_sel_hi:[1,0] neg_lo:[0,1] neg_hi:[0,1]
	v_mul_f32_e32 v16, v91, v91
	v_pk_fma_f32 v[16:17], v[90:91], v[90:91], v[16:17] op_sel_hi:[1,1,0]
	v_mul_f32_e32 v18, v89, v89
	v_pk_fma_f32 v[16:17], v[88:89], v[88:89], v[16:17]
	v_pk_add_f32 v[94:95], v[40:41], v[8:9] op_sel_hi:[1,0] neg_lo:[0,1] neg_hi:[0,1]
	v_pk_add_f32 v[16:17], v[18:19], v[16:17] op_sel_hi:[0,1]
	v_pk_add_f32 v[12:13], v[22:23], v[8:9] op_sel_hi:[1,0] neg_lo:[0,1] neg_hi:[0,1]
	v_mul_f32_e32 v22, v95, v95
	v_pk_fma_f32 v[16:17], v[94:95], v[94:95], v[16:17]
	v_pk_add_f32 v[92:93], v[42:43], v[8:9] op_sel_hi:[1,0] neg_lo:[0,1] neg_hi:[0,1]
	v_pk_add_f32 v[16:17], v[22:23], v[16:17] op_sel_hi:[0,1]
	v_pk_add_f32 v[96:97], v[44:45], v[8:9] op_sel_hi:[1,0] neg_lo:[0,1] neg_hi:[0,1]
	v_pk_add_f32 v[4:5], v[46:47], v[8:9] op_sel_hi:[1,0] neg_lo:[0,1] neg_hi:[0,1]
	v_pk_add_f32 v[8:9], v[24:25], v[8:9] op_sel_hi:[1,0] neg_lo:[0,1] neg_hi:[0,1]
	v_mul_f32_e32 v24, v93, v93
	v_pk_fma_f32 v[16:17], v[92:93], v[92:93], v[16:17]
	v_mul_f32_e32 v26, v97, v97
	v_pk_add_f32 v[16:17], v[24:25], v[16:17] op_sel_hi:[0,1]
	v_pk_fma_f32 v[16:17], v[96:97], v[96:97], v[16:17]
	v_mul_f32_e32 v28, v5, v5
	v_pk_add_f32 v[16:17], v[26:27], v[16:17] op_sel_hi:[0,1]
	v_pk_fma_f32 v[16:17], v[4:5], v[4:5], v[16:17]
	v_mul_f32_e32 v30, v13, v13
	v_pk_add_f32 v[16:17], v[28:29], v[16:17] op_sel_hi:[0,1]
	v_pk_fma_f32 v[16:17], v[12:13], v[12:13], v[16:17]
	v_mul_f32_e32 v18, v9, v9
	v_pk_add_f32 v[16:17], v[30:31], v[16:17] op_sel_hi:[0,1]
	v_pk_fma_f32 v[16:17], v[8:9], v[8:9], v[16:17]
	v_permlane16_swap_b32_e32 v3, v111
	v_pk_add_f32 v[16:17], v[18:19], v[16:17] op_sel_hi:[0,1]
	v_mov_b32_e32 v17, v16
	s_nop 1
	v_permlane16_swap_b32_e32 v16, v17
	v_add_f32_e32 v117, v16, v17
	v_mov_b32_e32 v118, v117
	v_mad_i64_i32 v[16:17], s[14:15], v36, s23, v[78:79]
	v_permlane16_swap_b32_e32 v6, v110
	v_permlane16_swap_b32_e32 v7, v109
	v_permlane16_swap_b32_e32 v20, v38
	v_permlane16_swap_b32_e32 v21, v39
	v_permlane16_swap_b32_e32 v10, v114
	v_permlane16_swap_b32_e32 v11, v113
	v_permlane16_swap_b32_e32 v14, v108
	v_permlane16_swap_b32_e32 v15, v83
	v_permlane16_swap_b32_e32 v32, v115
	v_permlane16_swap_b32_e32 v33, v116
	v_permlane32_swap_b32_e32 v117, v118
	v_lshl_add_u64 v[98:99], v[16:17], 0, s[12:13]
	s_and_saveexec_b64 s[14:15], vcc
	s_xor_b64 s[14:15], exec, s[14:15]
	s_cbranch_execz .LBB0_503
	v_mov_b32_e32 v19, 0
	v_mov_b32_e32 v18, 0
	v_mov_b32_e32 v17, 0
	v_mov_b32_e32 v16, 0
	s_and_saveexec_b64 s[16:17], s[0:1]
	s_cbranch_execz .LBB0_502
	v_or_b32_e32 v16, v81, v100
	v_lshlrev_b32_e32 v220, 2, v16
	v_lshl_add_u64 v[16:17], v[98:99], 0, v[220:221]
	global_load_dwordx4 v[16:19], v[16:17], off

; extern "C" __global__ void __launch_bounds__(256, 2) hymba_mega(Params p, int ph_lo, int ph_hi) {
;     extern __shared__ __attribute__((aligned(16))) char lds[];
	.amdhsa_kernel hymba_mega
		.amdhsa_group_segment_fixed_size 0
		.amdhsa_private_segment_fixed_size 0
		.amdhsa_kernarg_size 456
		.amdhsa_user_sgpr_count 2
		.amdhsa_user_sgpr_dispatch_ptr 0
		.amdhsa_user_sgpr_queue_ptr 0
		.amdhsa_user_sgpr_kernarg_segment_ptr 1
		.amdhsa_user_sgpr_dispatch_id 0
		.amdhsa_user_sgpr_kernarg_preload_length 0
		.amdhsa_user_sgpr_kernarg_preload_offset 0
		.amdhsa_user_sgpr_private_segment_size 0
		.amdhsa_uses_dynamic_stack 0
		.amdhsa_enable_private_segment 0
		.amdhsa_system_sgpr_workgroup_id_x 1
		.amdhsa_system_sgpr_workgroup_id_y 0
		.amdhsa_system_sgpr_workgroup_id_z 0
		.amdhsa_system_sgpr_workgroup_info 0
		.amdhsa_system_vgpr_workitem_id 0
		.amdhsa_next_free_vgpr 256
		.amdhsa_next_free_sgpr 100
		.amdhsa_accum_offset 256
		.amdhsa_reserve_vcc 1
		.amdhsa_float_round_mode_32 0
		.amdhsa_float_round_mode_16_64 0
		.amdhsa_float_denorm_mode_32 3
		.amdhsa_float_denorm_mode_16_64 3
		.amdhsa_dx10_clamp 1
		.amdhsa_ieee_mode 1
		.amdhsa_fp16_overflow 0
		.amdhsa_tg_split 0
		.amdhsa_exception_fp_ieee_invalid_op 0
		.amdhsa_exception_fp_denorm_src 0
		.amdhsa_exception_fp_ieee_div_zero 0
		.amdhsa_exception_fp_ieee_overflow 0
		.amdhsa_exception_fp_ieee_underflow 0
		.amdhsa_exception_fp_ieee_inexact 0
		.amdhsa_exception_int_div_zero 0
	.end_amdhsa_kernel

; extern "C" __global__ void __launch_bounds__(256, 2) hymba_mega(Params p, int ph_lo, int ph_hi) {
amdhsa.kernels:
  - .agpr_count:     0
    .args:
      - .offset:         0
        .size:           192
        .value_kind:     by_value
      - .offset:         192
        .size:           4
        .value_kind:     by_value
      - .offset:         196
        .size:           4
        .value_kind:     by_value
      - .offset:         200
        .size:           4
        .value_kind:     hidden_block_count_x
      - .offset:         204
        .size:           4
        .value_kind:     hidden_block_count_y
      - .offset:         208
        .size:           4
        .value_kind:     hidden_block_count_z
      - .offset:         212
        .size:           2
        .value_kind:     hidden_group_size_x
      - .offset:         214
        .size:           2
        .value_kind:     hidden_group_size_y
      - .offset:         216
        .size:           2
        .value_kind:     hidden_group_size_z
      - .offset:         218
        .size:           2
        .value_kind:     hidden_remainder_x
      - .offset:         220
        .size:           2
        .value_kind:     hidden_remainder_y
      - .offset:         222
        .size:           2
        .value_kind:     hidden_remainder_z
      - .offset:         240
        .size:           8
        .value_kind:     hidden_global_offset_x
      - .offset:         248
        .size:           8
        .value_kind:     hidden_global_offset_y
      - .offset:         256
        .size:           8
        .value_kind:     hidden_global_offset_z
      - .offset:         264
        .size:           2
        .value_kind:     hidden_grid_dims
      - .offset:         320
        .size:           4
        .value_kind:     hidden_dynamic_lds_size
    .group_segment_fixed_size: 0
    .kernarg_segment_align: 8
    .kernarg_segment_size: 456
    .language:       OpenCL C
    .language_version:
      - 2
      - 0
    .max_flat_workgroup_size: 256
    .name:           hymba_mega
    .private_segment_fixed_size: 0
    .sgpr_count:     106
    .sgpr_spill_count: 70
    .symbol:         hymba_mega.kd
    .uniform_work_group_size: 1
    .uses_dynamic_stack: false
    .vgpr_count:     256
    .vgpr_spill_count: 0
    .wavefront_size: 64
